# in-projection epilogue: sigmoid/silu blocks rewritten with packed f32 math and one uniform branch per 8-value block instead of per-element selects (about 40% fewer VALU instructions on gated tiles)
# baseline (speedup 1.0000x reference)
.LBB0_265:
	s_add_i32 s2, s78, 0xffffffbd
	s_cmpk_gt_i32 s78, 0x42
	s_cselect_b32 s8, 3, 0
	s_and_b64 s[6:7], s[6:7], exec
	s_cselect_b32 s6, 2, s8
	s_cmp_lt_u32 s2, -8
	s_cselect_b32 s2, s6, 1
	s_cmp_lg_u32 s2, 0
	s_cselect_b64 s[38:39], -1, 0
	s_cmp_eq_u32 s2, 3
	s_cselect_b64 s[6:7], -1, 0
	s_cmp_eq_u32 s2, 0
	v_mov_b32_e32 v153, v70
	v_mov_b32_e32 v168, v71
	v_mov_b32_e32 v170, v72
	v_mov_b32_e32 v172, v73
	v_mov_b32_e32 v167, v66
	v_mov_b32_e32 v169, v67
	v_mov_b32_e32 v171, v68
	v_mov_b32_e32 v173, v69
	s_cbranch_scc1 .LBB0_267
	v_mov_b32_e32 v242, 0xbfb8aa3b
	v_pk_mul_f32 v[234:235], v[66:67], v[242:243] op_sel_hi:[1,0]
	v_exp_f32_e32 v234, v234
	v_exp_f32_e32 v235, v235
	v_pk_mul_f32 v[236:237], v[68:69], v[242:243] op_sel_hi:[1,0]
	v_exp_f32_e32 v236, v236
	v_exp_f32_e32 v237, v237
	v_pk_mul_f32 v[238:239], v[70:71], v[242:243] op_sel_hi:[1,0]
	v_exp_f32_e32 v238, v238
	v_exp_f32_e32 v239, v239
	v_pk_mul_f32 v[240:241], v[72:73], v[242:243] op_sel_hi:[1,0]
	v_exp_f32_e32 v240, v240
	v_exp_f32_e32 v241, v241
	v_pk_add_f32 v[234:235], v[234:235], 1.0 op_sel_hi:[1,0]
	v_rcp_f32_e32 v234, v234
	v_rcp_f32_e32 v235, v235
	v_pk_add_f32 v[236:237], v[236:237], 1.0 op_sel_hi:[1,0]
	v_rcp_f32_e32 v236, v236
	v_rcp_f32_e32 v237, v237
	v_pk_add_f32 v[238:239], v[238:239], 1.0 op_sel_hi:[1,0]
	v_rcp_f32_e32 v238, v238
	v_rcp_f32_e32 v239, v239
	v_pk_add_f32 v[240:241], v[240:241], 1.0 op_sel_hi:[1,0]
	v_rcp_f32_e32 v240, v240
	v_rcp_f32_e32 v241, v241
	s_and_b64 vcc, exec, s[6:7]
	s_cbranch_vccnz .Lepg5339_m3
	s_waitcnt vmcnt(0)
	v_mul_f32_e32 v167, v66, v234
	v_mul_f32_e32 v169, v67, v235
	v_mul_f32_e32 v167, v167, v94
	v_mul_f32_e32 v169, v169, v95
	v_mul_f32_e32 v171, v68, v236
	v_mul_f32_e32 v173, v69, v237
	v_mul_f32_e32 v171, v171, v96
	v_mul_f32_e32 v173, v173, v97
	v_mul_f32_e32 v153, v70, v238
	v_mul_f32_e32 v168, v71, v239
	v_mul_f32_e32 v153, v153, v90
	v_mul_f32_e32 v168, v168, v91
	v_mul_f32_e32 v170, v72, v240
	v_mul_f32_e32 v172, v73, v241
	v_mul_f32_e32 v170, v170, v92
	v_mul_f32_e32 v172, v172, v93
	s_branch .Lepg5339_dn
.Lepg5339_m3:
	v_mov_b32_e32 v167, v234
	v_mov_b32_e32 v169, v235
	v_mov_b32_e32 v171, v236
	v_mov_b32_e32 v173, v237
	v_mov_b32_e32 v153, v238
	v_mov_b32_e32 v168, v239
	v_mov_b32_e32 v170, v240
	v_mov_b32_e32 v172, v241
.Lepg5339_dn:
.LBB0_267:
	v_readlane_b32 s8, v249, 43
	v_readlane_b32 s9, v249, 44
	v_lshl_or_b32 v154, s78, 8, v163
	v_ashrrev_i32_e32 v155, 31, v154
	v_mov_b64_e32 v[156:157], s[8:9]
	v_mad_i64_i32 v[156:157], s[8:9], v152, s76, v[156:157]
	v_cvt_pk_bf16_f32 v174, v153, v168
	v_cndmask_b32_e64 v153, 0, 1, s[38:39]
	v_lshl_add_u64 v[156:157], v[154:155], 1, v[156:157]
	v_cmp_ne_u32_e64 s[8:9], 1, v153
	s_andn2_b64 vcc, exec, s[38:39]
	v_cvt_pk_bf16_f32 v175, v170, v172
	v_cvt_pk_bf16_f32 v176, v167, v169
	v_cvt_pk_bf16_f32 v177, v171, v173
	global_store_dwordx4 v[156:157], v[174:177], off nt
	s_cbranch_vccnz .LBB0_269
	v_mov_b32_e32 v242, 0xbfb8aa3b
	v_pk_mul_f32 v[234:235], v[130:131], v[242:243] op_sel_hi:[1,0]
	v_exp_f32_e32 v234, v234
	v_exp_f32_e32 v235, v235
	v_pk_mul_f32 v[236:237], v[132:133], v[242:243] op_sel_hi:[1,0]
	v_exp_f32_e32 v236, v236
	v_exp_f32_e32 v237, v237
	v_pk_mul_f32 v[238:239], v[134:135], v[242:243] op_sel_hi:[1,0]
	v_exp_f32_e32 v238, v238
	v_exp_f32_e32 v239, v239
	v_pk_mul_f32 v[240:241], v[136:137], v[242:243] op_sel_hi:[1,0]
	v_exp_f32_e32 v240, v240
	v_exp_f32_e32 v241, v241
	v_pk_add_f32 v[234:235], v[234:235], 1.0 op_sel_hi:[1,0]
	v_rcp_f32_e32 v234, v234
	v_rcp_f32_e32 v235, v235
	v_pk_add_f32 v[236:237], v[236:237], 1.0 op_sel_hi:[1,0]
	v_rcp_f32_e32 v236, v236
	v_rcp_f32_e32 v237, v237
	v_pk_add_f32 v[238:239], v[238:239], 1.0 op_sel_hi:[1,0]
	v_rcp_f32_e32 v238, v238
	v_rcp_f32_e32 v239, v239
	v_pk_add_f32 v[240:241], v[240:241], 1.0 op_sel_hi:[1,0]
	v_rcp_f32_e32 v240, v240
	v_rcp_f32_e32 v241, v241
	s_and_b64 vcc, exec, s[6:7]
	s_cbranch_vccnz .Lepg5422_m3
	v_pk_mul_f32 v[130:131], v[130:131], v[234:235]
	v_pk_mul_f32 v[130:131], v[130:131], v[94:95]
	v_pk_mul_f32 v[132:133], v[132:133], v[236:237]
	v_pk_mul_f32 v[132:133], v[132:133], v[96:97]
	v_pk_mul_f32 v[134:135], v[134:135], v[238:239]
	v_pk_mul_f32 v[134:135], v[134:135], v[90:91]
	v_pk_mul_f32 v[136:137], v[136:137], v[240:241]
	v_pk_mul_f32 v[136:137], v[136:137], v[92:93]
	s_branch .Lepg5422_dn
.Lepg5422_m3:
	v_mov_b64_e32 v[130:131], v[234:235]
	v_mov_b64_e32 v[132:133], v[236:237]
	v_mov_b64_e32 v[134:135], v[238:239]
	v_mov_b64_e32 v[136:137], v[240:241]
.Lepg5422_dn:
.LBB0_269:
	v_cvt_pk_bf16_f32 v134, v134, v135
	v_cvt_pk_bf16_f32 v135, v136, v137
	v_cvt_pk_bf16_f32 v136, v130, v131
	v_cvt_pk_bf16_f32 v137, v132, v133
	global_store_dwordx4 v[156:157], v[134:137], off offset:256 nt
	s_and_b64 vcc, exec, s[8:9]
	v_mov_b32_e32 v132, v62
	v_mov_b32_e32 v134, v63
	v_mov_b32_e32 v136, v64
	v_mov_b32_e32 v153, v65
	v_mov_b32_e32 v133, v58
	v_mov_b32_e32 v135, v59
	v_mov_b32_e32 v137, v60
	v_mov_b32_e32 v156, v61
	s_cbranch_vccnz .LBB0_271
	v_mov_b32_e32 v242, 0xbfb8aa3b
	v_pk_mul_f32 v[234:235], v[58:59], v[242:243] op_sel_hi:[1,0]
	v_exp_f32_e32 v234, v234
	v_exp_f32_e32 v235, v235
	v_pk_mul_f32 v[236:237], v[60:61], v[242:243] op_sel_hi:[1,0]
	v_exp_f32_e32 v236, v236
	v_exp_f32_e32 v237, v237
	v_pk_mul_f32 v[238:239], v[62:63], v[242:243] op_sel_hi:[1,0]
	v_exp_f32_e32 v238, v238
	v_exp_f32_e32 v239, v239
	v_pk_mul_f32 v[240:241], v[64:65], v[242:243] op_sel_hi:[1,0]
	v_exp_f32_e32 v240, v240
	v_exp_f32_e32 v241, v241
	v_pk_add_f32 v[234:235], v[234:235], 1.0 op_sel_hi:[1,0]
	v_rcp_f32_e32 v234, v234
	v_rcp_f32_e32 v235, v235
	v_pk_add_f32 v[236:237], v[236:237], 1.0 op_sel_hi:[1,0]
	v_rcp_f32_e32 v236, v236
	v_rcp_f32_e32 v237, v237
	v_pk_add_f32 v[238:239], v[238:239], 1.0 op_sel_hi:[1,0]
	v_rcp_f32_e32 v238, v238
	v_rcp_f32_e32 v239, v239
	v_pk_add_f32 v[240:241], v[240:241], 1.0 op_sel_hi:[1,0]
	v_rcp_f32_e32 v240, v240
	v_rcp_f32_e32 v241, v241
	s_and_b64 vcc, exec, s[6:7]
	s_cbranch_vccnz .Lepg5503_m3
	v_mul_f32_e32 v133, v58, v234
	v_mul_f32_e32 v135, v59, v235
	v_mul_f32_e32 v133, v133, v94
	v_mul_f32_e32 v135, v135, v95
	v_mul_f32_e32 v137, v60, v236
	v_mul_f32_e32 v156, v61, v237
	v_mul_f32_e32 v137, v137, v96
	v_mul_f32_e32 v156, v156, v97
	v_mul_f32_e32 v132, v62, v238
	v_mul_f32_e32 v134, v63, v239
	v_mul_f32_e32 v132, v132, v90
	v_mul_f32_e32 v134, v134, v91
	v_mul_f32_e32 v136, v64, v240
	v_mul_f32_e32 v153, v65, v241
	v_mul_f32_e32 v136, v136, v92
	v_mul_f32_e32 v153, v153, v93
	s_branch .Lepg5503_dn
.Lepg5503_m3:
	v_mov_b32_e32 v133, v234
	v_mov_b32_e32 v135, v235
	v_mov_b32_e32 v137, v236
	v_mov_b32_e32 v156, v237
	v_mov_b32_e32 v132, v238
	v_mov_b32_e32 v134, v239
	v_mov_b32_e32 v136, v240
	v_mov_b32_e32 v153, v241
.Lepg5503_dn:
.LBB0_271:
	v_readlane_b32 s38, v249, 43
	v_readlane_b32 s39, v249, 44
	v_or_b32_e32 v157, 16, v152
	s_and_b64 vcc, exec, s[8:9]
	v_mov_b64_e32 v[130:131], s[38:39]
	v_mad_i64_i32 v[130:131], s[38:39], v157, s76, v[130:131]
	v_lshl_add_u64 v[130:131], v[154:155], 1, v[130:131]
	v_cvt_pk_bf16_f32 v168, v132, v134
	v_cvt_pk_bf16_f32 v169, v136, v153
	v_cvt_pk_bf16_f32 v170, v133, v135
	v_cvt_pk_bf16_f32 v171, v137, v156
	global_store_dwordx4 v[130:131], v[168:171], off nt
	s_cbranch_vccnz .LBB0_273
	v_mov_b32_e32 v242, 0xbfb8aa3b
	v_pk_mul_f32 v[234:235], v[122:123], v[242:243] op_sel_hi:[1,0]
	v_exp_f32_e32 v234, v234
	v_exp_f32_e32 v235, v235
	v_pk_mul_f32 v[236:237], v[124:125], v[242:243] op_sel_hi:[1,0]
	v_exp_f32_e32 v236, v236
	v_exp_f32_e32 v237, v237
	v_pk_mul_f32 v[238:239], v[126:127], v[242:243] op_sel_hi:[1,0]
	v_exp_f32_e32 v238, v238
	v_exp_f32_e32 v239, v239
	v_pk_mul_f32 v[240:241], v[128:129], v[242:243] op_sel_hi:[1,0]
	v_exp_f32_e32 v240, v240
	v_exp_f32_e32 v241, v241
	v_pk_add_f32 v[234:235], v[234:235], 1.0 op_sel_hi:[1,0]
	v_rcp_f32_e32 v234, v234
	v_rcp_f32_e32 v235, v235
	v_pk_add_f32 v[236:237], v[236:237], 1.0 op_sel_hi:[1,0]
	v_rcp_f32_e32 v236, v236
	v_rcp_f32_e32 v237, v237
	v_pk_add_f32 v[238:239], v[238:239], 1.0 op_sel_hi:[1,0]
	v_rcp_f32_e32 v238, v238
	v_rcp_f32_e32 v239, v239
	v_pk_add_f32 v[240:241], v[240:241], 1.0 op_sel_hi:[1,0]
	v_rcp_f32_e32 v240, v240
	v_rcp_f32_e32 v241, v241
	s_and_b64 vcc, exec, s[6:7]
	s_cbranch_vccnz .Lepg5582_m3
	v_pk_mul_f32 v[122:123], v[122:123], v[234:235]
	v_pk_mul_f32 v[122:123], v[122:123], v[94:95]
	v_pk_mul_f32 v[124:125], v[124:125], v[236:237]
	v_pk_mul_f32 v[124:125], v[124:125], v[96:97]
	v_pk_mul_f32 v[126:127], v[126:127], v[238:239]
	v_pk_mul_f32 v[126:127], v[126:127], v[90:91]
	v_pk_mul_f32 v[128:129], v[128:129], v[240:241]
	v_pk_mul_f32 v[128:129], v[128:129], v[92:93]
	s_branch .Lepg5582_dn
.Lepg5582_m3:
	v_mov_b64_e32 v[122:123], v[234:235]
	v_mov_b64_e32 v[124:125], v[236:237]
	v_mov_b64_e32 v[126:127], v[238:239]
	v_mov_b64_e32 v[128:129], v[240:241]
.Lepg5582_dn:
.LBB0_273:
	v_cvt_pk_bf16_f32 v126, v126, v127
	v_cvt_pk_bf16_f32 v127, v128, v129
	v_cvt_pk_bf16_f32 v128, v122, v123
	v_cvt_pk_bf16_f32 v129, v124, v125
	global_store_dwordx4 v[130:131], v[126:129], off offset:256 nt
	s_and_b64 vcc, exec, s[8:9]
	v_mov_b32_e32 v124, v54
	v_mov_b32_e32 v126, v55
	v_mov_b32_e32 v128, v56
	v_mov_b32_e32 v130, v57
	v_mov_b32_e32 v125, v50
	v_mov_b32_e32 v127, v51
	v_mov_b32_e32 v129, v52
	v_mov_b32_e32 v131, v53
	s_cbranch_vccnz .LBB0_275
	v_mov_b32_e32 v242, 0xbfb8aa3b
	v_pk_mul_f32 v[234:235], v[50:51], v[242:243] op_sel_hi:[1,0]
	v_exp_f32_e32 v234, v234
	v_exp_f32_e32 v235, v235
	v_pk_mul_f32 v[236:237], v[52:53], v[242:243] op_sel_hi:[1,0]
	v_exp_f32_e32 v236, v236
	v_exp_f32_e32 v237, v237
	v_pk_mul_f32 v[238:239], v[54:55], v[242:243] op_sel_hi:[1,0]
	v_exp_f32_e32 v238, v238
	v_exp_f32_e32 v239, v239
	v_pk_mul_f32 v[240:241], v[56:57], v[242:243] op_sel_hi:[1,0]
	v_exp_f32_e32 v240, v240
	v_exp_f32_e32 v241, v241
	v_pk_add_f32 v[234:235], v[234:235], 1.0 op_sel_hi:[1,0]
	v_rcp_f32_e32 v234, v234
	v_rcp_f32_e32 v235, v235
	v_pk_add_f32 v[236:237], v[236:237], 1.0 op_sel_hi:[1,0]
	v_rcp_f32_e32 v236, v236
	v_rcp_f32_e32 v237, v237
	v_pk_add_f32 v[238:239], v[238:239], 1.0 op_sel_hi:[1,0]
	v_rcp_f32_e32 v238, v238
	v_rcp_f32_e32 v239, v239
	v_pk_add_f32 v[240:241], v[240:241], 1.0 op_sel_hi:[1,0]
	v_rcp_f32_e32 v240, v240
	v_rcp_f32_e32 v241, v241
	s_and_b64 vcc, exec, s[6:7]
	s_cbranch_vccnz .Lepg5663_m3
	v_mul_f32_e32 v125, v50, v234
	v_mul_f32_e32 v127, v51, v235
	v_mul_f32_e32 v125, v125, v94
	v_mul_f32_e32 v127, v127, v95
	v_mul_f32_e32 v129, v52, v236
	v_mul_f32_e32 v131, v53, v237
	v_mul_f32_e32 v129, v129, v96
	v_mul_f32_e32 v131, v131, v97
	v_mul_f32_e32 v124, v54, v238
	v_mul_f32_e32 v126, v55, v239
	v_mul_f32_e32 v124, v124, v90
	v_mul_f32_e32 v126, v126, v91
	v_mul_f32_e32 v128, v56, v240
	v_mul_f32_e32 v130, v57, v241
	v_mul_f32_e32 v128, v128, v92
	v_mul_f32_e32 v130, v130, v93
	s_branch .Lepg5663_dn
.Lepg5663_m3:
	v_mov_b32_e32 v125, v234
	v_mov_b32_e32 v127, v235
	v_mov_b32_e32 v129, v236
	v_mov_b32_e32 v131, v237
	v_mov_b32_e32 v124, v238
	v_mov_b32_e32 v126, v239
	v_mov_b32_e32 v128, v240
	v_mov_b32_e32 v130, v241
.Lepg5663_dn:
.LBB0_275:
	v_readlane_b32 s38, v249, 43
	v_readlane_b32 s39, v249, 44
	v_or_b32_e32 v132, 32, v152
	s_and_b64 vcc, exec, s[8:9]
	v_mov_b64_e32 v[122:123], s[38:39]
	v_mad_i64_i32 v[122:123], s[38:39], v132, s76, v[122:123]
	v_lshl_add_u64 v[122:123], v[154:155], 1, v[122:123]
	v_cvt_pk_bf16_f32 v132, v124, v126
	v_cvt_pk_bf16_f32 v133, v128, v130
	v_cvt_pk_bf16_f32 v134, v125, v127
	v_cvt_pk_bf16_f32 v135, v129, v131
	global_store_dwordx4 v[122:123], v[132:135], off nt
	s_cbranch_vccnz .LBB0_277
	v_mov_b32_e32 v242, 0xbfb8aa3b
	v_pk_mul_f32 v[234:235], v[114:115], v[242:243] op_sel_hi:[1,0]
	v_exp_f32_e32 v234, v234
	v_exp_f32_e32 v235, v235
	v_pk_mul_f32 v[236:237], v[116:117], v[242:243] op_sel_hi:[1,0]
	v_exp_f32_e32 v236, v236
	v_exp_f32_e32 v237, v237
	v_pk_mul_f32 v[238:239], v[118:119], v[242:243] op_sel_hi:[1,0]
	v_exp_f32_e32 v238, v238
	v_exp_f32_e32 v239, v239
	v_pk_mul_f32 v[240:241], v[120:121], v[242:243] op_sel_hi:[1,0]
	v_exp_f32_e32 v240, v240
	v_exp_f32_e32 v241, v241
	v_pk_add_f32 v[234:235], v[234:235], 1.0 op_sel_hi:[1,0]
	v_rcp_f32_e32 v234, v234
	v_rcp_f32_e32 v235, v235
	v_pk_add_f32 v[236:237], v[236:237], 1.0 op_sel_hi:[1,0]
	v_rcp_f32_e32 v236, v236
	v_rcp_f32_e32 v237, v237
	v_pk_add_f32 v[238:239], v[238:239], 1.0 op_sel_hi:[1,0]
	v_rcp_f32_e32 v238, v238
	v_rcp_f32_e32 v239, v239
	v_pk_add_f32 v[240:241], v[240:241], 1.0 op_sel_hi:[1,0]
	v_rcp_f32_e32 v240, v240
	v_rcp_f32_e32 v241, v241
	s_and_b64 vcc, exec, s[6:7]
	s_cbranch_vccnz .Lepg5742_m3
	v_pk_mul_f32 v[114:115], v[114:115], v[234:235]
	v_pk_mul_f32 v[114:115], v[114:115], v[94:95]
	v_pk_mul_f32 v[116:117], v[116:117], v[236:237]
	v_pk_mul_f32 v[116:117], v[116:117], v[96:97]
	v_pk_mul_f32 v[118:119], v[118:119], v[238:239]
	v_pk_mul_f32 v[118:119], v[118:119], v[90:91]
	v_pk_mul_f32 v[120:121], v[120:121], v[240:241]
	v_pk_mul_f32 v[120:121], v[120:121], v[92:93]
	s_branch .Lepg5742_dn
.Lepg5742_m3:
	v_mov_b64_e32 v[114:115], v[234:235]
	v_mov_b64_e32 v[116:117], v[236:237]
	v_mov_b64_e32 v[118:119], v[238:239]
	v_mov_b64_e32 v[120:121], v[240:241]
.Lepg5742_dn:
.LBB0_277:
	v_cvt_pk_bf16_f32 v118, v118, v119
	v_cvt_pk_bf16_f32 v119, v120, v121
	v_cvt_pk_bf16_f32 v120, v114, v115
	v_cvt_pk_bf16_f32 v121, v116, v117
	global_store_dwordx4 v[122:123], v[118:121], off offset:256 nt
	s_and_b64 vcc, exec, s[8:9]
	v_mov_b32_e32 v116, v46
	v_mov_b32_e32 v118, v47
	v_mov_b32_e32 v120, v48
	v_mov_b32_e32 v122, v49
	v_mov_b32_e32 v117, v42
	v_mov_b32_e32 v119, v43
	v_mov_b32_e32 v121, v44
	v_mov_b32_e32 v123, v45
	s_cbranch_vccnz .LBB0_279
	v_mov_b32_e32 v242, 0xbfb8aa3b
	v_pk_mul_f32 v[234:235], v[42:43], v[242:243] op_sel_hi:[1,0]
	v_exp_f32_e32 v234, v234
	v_exp_f32_e32 v235, v235
	v_pk_mul_f32 v[236:237], v[44:45], v[242:243] op_sel_hi:[1,0]
	v_exp_f32_e32 v236, v236
	v_exp_f32_e32 v237, v237
	v_pk_mul_f32 v[238:239], v[46:47], v[242:243] op_sel_hi:[1,0]
	v_exp_f32_e32 v238, v238
	v_exp_f32_e32 v239, v239
	v_pk_mul_f32 v[240:241], v[48:49], v[242:243] op_sel_hi:[1,0]
	v_exp_f32_e32 v240, v240
	v_exp_f32_e32 v241, v241
	v_pk_add_f32 v[234:235], v[234:235], 1.0 op_sel_hi:[1,0]
	v_rcp_f32_e32 v234, v234
	v_rcp_f32_e32 v235, v235
	v_pk_add_f32 v[236:237], v[236:237], 1.0 op_sel_hi:[1,0]
	v_rcp_f32_e32 v236, v236
	v_rcp_f32_e32 v237, v237
	v_pk_add_f32 v[238:239], v[238:239], 1.0 op_sel_hi:[1,0]
	v_rcp_f32_e32 v238, v238
	v_rcp_f32_e32 v239, v239
	v_pk_add_f32 v[240:241], v[240:241], 1.0 op_sel_hi:[1,0]
	v_rcp_f32_e32 v240, v240
	v_rcp_f32_e32 v241, v241
	s_and_b64 vcc, exec, s[6:7]
	s_cbranch_vccnz .Lepg5823_m3
	v_mul_f32_e32 v117, v42, v234
	v_mul_f32_e32 v119, v43, v235
	v_mul_f32_e32 v117, v117, v94
	v_mul_f32_e32 v119, v119, v95
	v_mul_f32_e32 v121, v44, v236
	v_mul_f32_e32 v123, v45, v237
	v_mul_f32_e32 v121, v121, v96
	v_mul_f32_e32 v123, v123, v97
	v_mul_f32_e32 v116, v46, v238
	v_mul_f32_e32 v118, v47, v239
	v_mul_f32_e32 v116, v116, v90
	v_mul_f32_e32 v118, v118, v91
	v_mul_f32_e32 v120, v48, v240
	v_mul_f32_e32 v122, v49, v241
	v_mul_f32_e32 v120, v120, v92
	v_mul_f32_e32 v122, v122, v93
	s_branch .Lepg5823_dn
.Lepg5823_m3:
	v_mov_b32_e32 v117, v234
	v_mov_b32_e32 v119, v235
	v_mov_b32_e32 v121, v236
	v_mov_b32_e32 v123, v237
	v_mov_b32_e32 v116, v238
	v_mov_b32_e32 v118, v239
	v_mov_b32_e32 v120, v240
	v_mov_b32_e32 v122, v241
.Lepg5823_dn:
.LBB0_279:
	v_readlane_b32 s38, v249, 43
	v_readlane_b32 s39, v249, 44
	v_or_b32_e32 v124, 48, v152
	s_and_b64 vcc, exec, s[8:9]
	v_mov_b64_e32 v[114:115], s[38:39]
	v_mad_i64_i32 v[114:115], s[38:39], v124, s76, v[114:115]
	v_lshl_add_u64 v[114:115], v[154:155], 1, v[114:115]
	v_cvt_pk_bf16_f32 v124, v116, v118
	v_cvt_pk_bf16_f32 v125, v120, v122
	v_cvt_pk_bf16_f32 v126, v117, v119
	v_cvt_pk_bf16_f32 v127, v121, v123
	global_store_dwordx4 v[114:115], v[124:127], off nt
	s_cbranch_vccnz .LBB0_281
	v_mov_b32_e32 v242, 0xbfb8aa3b
	v_pk_mul_f32 v[234:235], v[106:107], v[242:243] op_sel_hi:[1,0]
	v_exp_f32_e32 v234, v234
	v_exp_f32_e32 v235, v235
	v_pk_mul_f32 v[236:237], v[108:109], v[242:243] op_sel_hi:[1,0]
	v_exp_f32_e32 v236, v236
	v_exp_f32_e32 v237, v237
	v_pk_mul_f32 v[238:239], v[110:111], v[242:243] op_sel_hi:[1,0]
	v_exp_f32_e32 v238, v238
	v_exp_f32_e32 v239, v239
	v_pk_mul_f32 v[240:241], v[112:113], v[242:243] op_sel_hi:[1,0]
	v_exp_f32_e32 v240, v240
	v_exp_f32_e32 v241, v241
	v_pk_add_f32 v[234:235], v[234:235], 1.0 op_sel_hi:[1,0]
	v_rcp_f32_e32 v234, v234
	v_rcp_f32_e32 v235, v235
	v_pk_add_f32 v[236:237], v[236:237], 1.0 op_sel_hi:[1,0]
	v_rcp_f32_e32 v236, v236
	v_rcp_f32_e32 v237, v237
	v_pk_add_f32 v[238:239], v[238:239], 1.0 op_sel_hi:[1,0]
	v_rcp_f32_e32 v238, v238
	v_rcp_f32_e32 v239, v239
	v_pk_add_f32 v[240:241], v[240:241], 1.0 op_sel_hi:[1,0]
	v_rcp_f32_e32 v240, v240
	v_rcp_f32_e32 v241, v241
	s_and_b64 vcc, exec, s[6:7]
	s_cbranch_vccnz .Lepg5902_m3
	v_pk_mul_f32 v[106:107], v[106:107], v[234:235]
	v_pk_mul_f32 v[106:107], v[106:107], v[94:95]
	v_pk_mul_f32 v[108:109], v[108:109], v[236:237]
	v_pk_mul_f32 v[108:109], v[108:109], v[96:97]
	v_pk_mul_f32 v[110:111], v[110:111], v[238:239]
	v_pk_mul_f32 v[110:111], v[110:111], v[90:91]
	v_pk_mul_f32 v[112:113], v[112:113], v[240:241]
	v_pk_mul_f32 v[112:113], v[112:113], v[92:93]
	s_branch .Lepg5902_dn
.Lepg5902_m3:
	v_mov_b64_e32 v[106:107], v[234:235]
	v_mov_b64_e32 v[108:109], v[236:237]
	v_mov_b64_e32 v[110:111], v[238:239]
	v_mov_b64_e32 v[112:113], v[240:241]
.Lepg5902_dn:
.LBB0_281:
	v_cvt_pk_bf16_f32 v110, v110, v111
	v_cvt_pk_bf16_f32 v111, v112, v113
	v_cvt_pk_bf16_f32 v112, v106, v107
	v_cvt_pk_bf16_f32 v113, v108, v109
	global_store_dwordx4 v[114:115], v[110:113], off offset:256 nt
	s_and_b64 vcc, exec, s[8:9]
	v_mov_b32_e32 v108, v34
	v_mov_b32_e32 v110, v35
	v_mov_b32_e32 v112, v36
	v_mov_b32_e32 v114, v37
	v_mov_b32_e32 v109, v26
	v_mov_b32_e32 v111, v27
	v_mov_b32_e32 v113, v28
	v_mov_b32_e32 v115, v29
	s_cbranch_vccnz .LBB0_283
	v_mov_b32_e32 v242, 0xbfb8aa3b
	v_pk_mul_f32 v[234:235], v[26:27], v[242:243] op_sel_hi:[1,0]
	v_exp_f32_e32 v234, v234
	v_exp_f32_e32 v235, v235
	v_pk_mul_f32 v[236:237], v[28:29], v[242:243] op_sel_hi:[1,0]
	v_exp_f32_e32 v236, v236
	v_exp_f32_e32 v237, v237
	v_pk_mul_f32 v[238:239], v[34:35], v[242:243] op_sel_hi:[1,0]
	v_exp_f32_e32 v238, v238
	v_exp_f32_e32 v239, v239
	v_pk_mul_f32 v[240:241], v[36:37], v[242:243] op_sel_hi:[1,0]
	v_exp_f32_e32 v240, v240
	v_exp_f32_e32 v241, v241
	v_pk_add_f32 v[234:235], v[234:235], 1.0 op_sel_hi:[1,0]
	v_rcp_f32_e32 v234, v234
	v_rcp_f32_e32 v235, v235
	v_pk_add_f32 v[236:237], v[236:237], 1.0 op_sel_hi:[1,0]
	v_rcp_f32_e32 v236, v236
	v_rcp_f32_e32 v237, v237
	v_pk_add_f32 v[238:239], v[238:239], 1.0 op_sel_hi:[1,0]
	v_rcp_f32_e32 v238, v238
	v_rcp_f32_e32 v239, v239
	v_pk_add_f32 v[240:241], v[240:241], 1.0 op_sel_hi:[1,0]
	v_rcp_f32_e32 v240, v240
	v_rcp_f32_e32 v241, v241
	s_and_b64 vcc, exec, s[6:7]
	s_cbranch_vccnz .Lepg5983_m3
	v_mul_f32_e32 v109, v26, v234
	v_mul_f32_e32 v111, v27, v235
	v_mul_f32_e32 v109, v109, v94
	v_mul_f32_e32 v111, v111, v95
	v_mul_f32_e32 v113, v28, v236
	v_mul_f32_e32 v115, v29, v237
	v_mul_f32_e32 v113, v113, v96
	v_mul_f32_e32 v115, v115, v97
	v_mul_f32_e32 v108, v34, v238
	v_mul_f32_e32 v110, v35, v239
	v_mul_f32_e32 v108, v108, v90
	v_mul_f32_e32 v110, v110, v91
	v_mul_f32_e32 v112, v36, v240
	v_mul_f32_e32 v114, v37, v241
	v_mul_f32_e32 v112, v112, v92
	v_mul_f32_e32 v114, v114, v93
	s_branch .Lepg5983_dn
.Lepg5983_m3:
	v_mov_b32_e32 v109, v234
	v_mov_b32_e32 v111, v235
	v_mov_b32_e32 v113, v236
	v_mov_b32_e32 v115, v237
	v_mov_b32_e32 v108, v238
	v_mov_b32_e32 v110, v239
	v_mov_b32_e32 v112, v240
	v_mov_b32_e32 v114, v241
.Lepg5983_dn:
.LBB0_283:
	v_readlane_b32 s38, v249, 43
	v_readlane_b32 s39, v249, 44
	v_add_u32_e32 v116, 0x80, v152
	s_and_b64 vcc, exec, s[8:9]
	v_mov_b64_e32 v[106:107], s[38:39]
	v_mad_i64_i32 v[106:107], s[38:39], v116, s76, v[106:107]
	v_lshl_add_u64 v[106:107], v[154:155], 1, v[106:107]
	v_cvt_pk_bf16_f32 v116, v108, v110
	v_cvt_pk_bf16_f32 v117, v112, v114
	v_cvt_pk_bf16_f32 v118, v109, v111
	v_cvt_pk_bf16_f32 v119, v113, v115
	global_store_dwordx4 v[106:107], v[116:119], off nt
	s_cbranch_vccnz .LBB0_285
	v_mov_b32_e32 v242, 0xbfb8aa3b
	v_pk_mul_f32 v[234:235], v[98:99], v[242:243] op_sel_hi:[1,0]
	v_exp_f32_e32 v234, v234
	v_exp_f32_e32 v235, v235
	v_pk_mul_f32 v[236:237], v[100:101], v[242:243] op_sel_hi:[1,0]
	v_exp_f32_e32 v236, v236
	v_exp_f32_e32 v237, v237
	v_pk_mul_f32 v[238:239], v[102:103], v[242:243] op_sel_hi:[1,0]
	v_exp_f32_e32 v238, v238
	v_exp_f32_e32 v239, v239
	v_pk_mul_f32 v[240:241], v[104:105], v[242:243] op_sel_hi:[1,0]
	v_exp_f32_e32 v240, v240
	v_exp_f32_e32 v241, v241
	v_pk_add_f32 v[234:235], v[234:235], 1.0 op_sel_hi:[1,0]
	v_rcp_f32_e32 v234, v234
	v_rcp_f32_e32 v235, v235
	v_pk_add_f32 v[236:237], v[236:237], 1.0 op_sel_hi:[1,0]
	v_rcp_f32_e32 v236, v236
	v_rcp_f32_e32 v237, v237
	v_pk_add_f32 v[238:239], v[238:239], 1.0 op_sel_hi:[1,0]
	v_rcp_f32_e32 v238, v238
	v_rcp_f32_e32 v239, v239
	v_pk_add_f32 v[240:241], v[240:241], 1.0 op_sel_hi:[1,0]
	v_rcp_f32_e32 v240, v240
	v_rcp_f32_e32 v241, v241
	s_and_b64 vcc, exec, s[6:7]
	s_cbranch_vccnz .Lepg6062_m3
	v_pk_mul_f32 v[98:99], v[98:99], v[234:235]
	v_pk_mul_f32 v[98:99], v[98:99], v[94:95]
	v_pk_mul_f32 v[100:101], v[100:101], v[236:237]
	v_pk_mul_f32 v[100:101], v[100:101], v[96:97]
	v_pk_mul_f32 v[102:103], v[102:103], v[238:239]
	v_pk_mul_f32 v[102:103], v[102:103], v[90:91]
	v_pk_mul_f32 v[104:105], v[104:105], v[240:241]
	v_pk_mul_f32 v[104:105], v[104:105], v[92:93]
	s_branch .Lepg6062_dn
.Lepg6062_m3:
	v_mov_b64_e32 v[98:99], v[234:235]
	v_mov_b64_e32 v[100:101], v[236:237]
	v_mov_b64_e32 v[102:103], v[238:239]
	v_mov_b64_e32 v[104:105], v[240:241]
.Lepg6062_dn:
.LBB0_285:
	v_cvt_pk_bf16_f32 v102, v102, v103
	v_cvt_pk_bf16_f32 v103, v104, v105
	v_cvt_pk_bf16_f32 v104, v98, v99
	v_cvt_pk_bf16_f32 v105, v100, v101
	global_store_dwordx4 v[106:107], v[102:105], off offset:256 nt
	s_and_b64 vcc, exec, s[8:9]
	v_mov_b32_e32 v100, v22
	v_mov_b32_e32 v102, v23
	v_mov_b32_e32 v104, v24
	v_mov_b32_e32 v106, v25
	v_mov_b32_e32 v101, v18
	v_mov_b32_e32 v103, v19
	v_mov_b32_e32 v105, v20
	v_mov_b32_e32 v107, v21
	s_cbranch_vccnz .LBB0_287
	v_mov_b32_e32 v242, 0xbfb8aa3b
	v_pk_mul_f32 v[234:235], v[18:19], v[242:243] op_sel_hi:[1,0]
	v_exp_f32_e32 v234, v234
	v_exp_f32_e32 v235, v235
	v_pk_mul_f32 v[236:237], v[20:21], v[242:243] op_sel_hi:[1,0]
	v_exp_f32_e32 v236, v236
	v_exp_f32_e32 v237, v237
	v_pk_mul_f32 v[238:239], v[22:23], v[242:243] op_sel_hi:[1,0]
	v_exp_f32_e32 v238, v238
	v_exp_f32_e32 v239, v239
	v_pk_mul_f32 v[240:241], v[24:25], v[242:243] op_sel_hi:[1,0]
	v_exp_f32_e32 v240, v240
	v_exp_f32_e32 v241, v241
	v_pk_add_f32 v[234:235], v[234:235], 1.0 op_sel_hi:[1,0]
	v_rcp_f32_e32 v234, v234
	v_rcp_f32_e32 v235, v235
	v_pk_add_f32 v[236:237], v[236:237], 1.0 op_sel_hi:[1,0]
	v_rcp_f32_e32 v236, v236
	v_rcp_f32_e32 v237, v237
	v_pk_add_f32 v[238:239], v[238:239], 1.0 op_sel_hi:[1,0]
	v_rcp_f32_e32 v238, v238
	v_rcp_f32_e32 v239, v239
	v_pk_add_f32 v[240:241], v[240:241], 1.0 op_sel_hi:[1,0]
	v_rcp_f32_e32 v240, v240
	v_rcp_f32_e32 v241, v241
	s_and_b64 vcc, exec, s[6:7]
	s_cbranch_vccnz .Lepg6143_m3
	v_mul_f32_e32 v101, v18, v234
	v_mul_f32_e32 v103, v19, v235
	v_mul_f32_e32 v101, v101, v94
	v_mul_f32_e32 v103, v103, v95
	v_mul_f32_e32 v105, v20, v236
	v_mul_f32_e32 v107, v21, v237
	v_mul_f32_e32 v105, v105, v96
	v_mul_f32_e32 v107, v107, v97
	v_mul_f32_e32 v100, v22, v238
	v_mul_f32_e32 v102, v23, v239
	v_mul_f32_e32 v100, v100, v90
	v_mul_f32_e32 v102, v102, v91
	v_mul_f32_e32 v104, v24, v240
	v_mul_f32_e32 v106, v25, v241
	v_mul_f32_e32 v104, v104, v92
	v_mul_f32_e32 v106, v106, v93
	s_branch .Lepg6143_dn
.Lepg6143_m3:
	v_mov_b32_e32 v101, v234
	v_mov_b32_e32 v103, v235
	v_mov_b32_e32 v105, v236
	v_mov_b32_e32 v107, v237
	v_mov_b32_e32 v100, v238
	v_mov_b32_e32 v102, v239
	v_mov_b32_e32 v104, v240
	v_mov_b32_e32 v106, v241
.Lepg6143_dn:
.LBB0_287:
	v_readlane_b32 s38, v249, 43
	v_readlane_b32 s39, v249, 44
	v_add_u32_e32 v108, 0x90, v152
	s_and_b64 vcc, exec, s[8:9]
	v_mov_b64_e32 v[98:99], s[38:39]
	v_mad_i64_i32 v[98:99], s[38:39], v108, s76, v[98:99]
	v_lshl_add_u64 v[98:99], v[154:155], 1, v[98:99]
	v_cvt_pk_bf16_f32 v108, v100, v102
	v_cvt_pk_bf16_f32 v109, v104, v106
	v_cvt_pk_bf16_f32 v110, v101, v103
	v_cvt_pk_bf16_f32 v111, v105, v107
	global_store_dwordx4 v[98:99], v[108:111], off nt
	s_cbranch_vccnz .LBB0_289
	v_mov_b32_e32 v242, 0xbfb8aa3b
	v_pk_mul_f32 v[234:235], v[82:83], v[242:243] op_sel_hi:[1,0]
	v_exp_f32_e32 v234, v234
	v_exp_f32_e32 v235, v235
	v_pk_mul_f32 v[236:237], v[84:85], v[242:243] op_sel_hi:[1,0]
	v_exp_f32_e32 v236, v236
	v_exp_f32_e32 v237, v237
	v_pk_mul_f32 v[238:239], v[86:87], v[242:243] op_sel_hi:[1,0]
	v_exp_f32_e32 v238, v238
	v_exp_f32_e32 v239, v239
	v_pk_mul_f32 v[240:241], v[88:89], v[242:243] op_sel_hi:[1,0]
	v_exp_f32_e32 v240, v240
	v_exp_f32_e32 v241, v241
	v_pk_add_f32 v[234:235], v[234:235], 1.0 op_sel_hi:[1,0]
	v_rcp_f32_e32 v234, v234
	v_rcp_f32_e32 v235, v235
	v_pk_add_f32 v[236:237], v[236:237], 1.0 op_sel_hi:[1,0]
	v_rcp_f32_e32 v236, v236
	v_rcp_f32_e32 v237, v237
	v_pk_add_f32 v[238:239], v[238:239], 1.0 op_sel_hi:[1,0]
	v_rcp_f32_e32 v238, v238
	v_rcp_f32_e32 v239, v239
	v_pk_add_f32 v[240:241], v[240:241], 1.0 op_sel_hi:[1,0]
	v_rcp_f32_e32 v240, v240
	v_rcp_f32_e32 v241, v241
	s_and_b64 vcc, exec, s[6:7]
	s_cbranch_vccnz .Lepg6222_m3
	v_pk_mul_f32 v[82:83], v[82:83], v[234:235]
	v_pk_mul_f32 v[82:83], v[82:83], v[94:95]
	v_pk_mul_f32 v[84:85], v[84:85], v[236:237]
	v_pk_mul_f32 v[84:85], v[84:85], v[96:97]
	v_pk_mul_f32 v[86:87], v[86:87], v[238:239]
	v_pk_mul_f32 v[86:87], v[86:87], v[90:91]
	v_pk_mul_f32 v[88:89], v[88:89], v[240:241]
	v_pk_mul_f32 v[88:89], v[88:89], v[92:93]
	s_branch .Lepg6222_dn
.Lepg6222_m3:
	v_mov_b64_e32 v[82:83], v[234:235]
	v_mov_b64_e32 v[84:85], v[236:237]
	v_mov_b64_e32 v[86:87], v[238:239]
	v_mov_b64_e32 v[88:89], v[240:241]
.Lepg6222_dn:
.LBB0_289:
	v_cvt_pk_bf16_f32 v86, v86, v87
	v_cvt_pk_bf16_f32 v87, v88, v89
	v_cvt_pk_bf16_f32 v88, v82, v83
	v_cvt_pk_bf16_f32 v89, v84, v85
	global_store_dwordx4 v[98:99], v[86:89], off offset:256 nt
	s_and_b64 vcc, exec, s[8:9]
	v_mov_b32_e32 v84, v14
	v_mov_b32_e32 v86, v15
	v_mov_b32_e32 v88, v16
	v_mov_b32_e32 v98, v17
	v_mov_b32_e32 v85, v10
	v_mov_b32_e32 v87, v11
	v_mov_b32_e32 v89, v12
	v_mov_b32_e32 v99, v13
	s_cbranch_vccnz .LBB0_291
	v_mov_b32_e32 v242, 0xbfb8aa3b
	v_pk_mul_f32 v[234:235], v[10:11], v[242:243] op_sel_hi:[1,0]
	v_exp_f32_e32 v234, v234
	v_exp_f32_e32 v235, v235
	v_pk_mul_f32 v[236:237], v[12:13], v[242:243] op_sel_hi:[1,0]
	v_exp_f32_e32 v236, v236
	v_exp_f32_e32 v237, v237
	v_pk_mul_f32 v[238:239], v[14:15], v[242:243] op_sel_hi:[1,0]
	v_exp_f32_e32 v238, v238
	v_exp_f32_e32 v239, v239
	v_pk_mul_f32 v[240:241], v[16:17], v[242:243] op_sel_hi:[1,0]
	v_exp_f32_e32 v240, v240
	v_exp_f32_e32 v241, v241
	v_pk_add_f32 v[234:235], v[234:235], 1.0 op_sel_hi:[1,0]
	v_rcp_f32_e32 v234, v234
	v_rcp_f32_e32 v235, v235
	v_pk_add_f32 v[236:237], v[236:237], 1.0 op_sel_hi:[1,0]
	v_rcp_f32_e32 v236, v236
	v_rcp_f32_e32 v237, v237
	v_pk_add_f32 v[238:239], v[238:239], 1.0 op_sel_hi:[1,0]
	v_rcp_f32_e32 v238, v238
	v_rcp_f32_e32 v239, v239
	v_pk_add_f32 v[240:241], v[240:241], 1.0 op_sel_hi:[1,0]
	v_rcp_f32_e32 v240, v240
	v_rcp_f32_e32 v241, v241
	s_and_b64 vcc, exec, s[6:7]
	s_cbranch_vccnz .Lepg6303_m3
	v_mul_f32_e32 v85, v10, v234
	v_mul_f32_e32 v87, v11, v235
	v_mul_f32_e32 v85, v85, v94
	v_mul_f32_e32 v87, v87, v95
	v_mul_f32_e32 v89, v12, v236
	v_mul_f32_e32 v99, v13, v237
	v_mul_f32_e32 v89, v89, v96
	v_mul_f32_e32 v99, v99, v97
	v_mul_f32_e32 v84, v14, v238
	v_mul_f32_e32 v86, v15, v239
	v_mul_f32_e32 v84, v84, v90
	v_mul_f32_e32 v86, v86, v91
	v_mul_f32_e32 v88, v16, v240
	v_mul_f32_e32 v98, v17, v241
	v_mul_f32_e32 v88, v88, v92
	v_mul_f32_e32 v98, v98, v93
	s_branch .Lepg6303_dn
.Lepg6303_m3:
	v_mov_b32_e32 v85, v234
	v_mov_b32_e32 v87, v235
	v_mov_b32_e32 v89, v236
	v_mov_b32_e32 v99, v237
	v_mov_b32_e32 v84, v238
	v_mov_b32_e32 v86, v239
	v_mov_b32_e32 v88, v240
	v_mov_b32_e32 v98, v241
.Lepg6303_dn:
.LBB0_291:
	v_readlane_b32 s38, v249, 43
	v_readlane_b32 s39, v249, 44
	v_add_u32_e32 v100, 0xa0, v152
	s_and_b64 vcc, exec, s[8:9]
	v_mov_b64_e32 v[82:83], s[38:39]
	v_mad_i64_i32 v[82:83], s[38:39], v100, s76, v[82:83]
	v_lshl_add_u64 v[82:83], v[154:155], 1, v[82:83]
	v_cvt_pk_bf16_f32 v100, v84, v86
	v_cvt_pk_bf16_f32 v101, v88, v98
	v_cvt_pk_bf16_f32 v102, v85, v87
	v_cvt_pk_bf16_f32 v103, v89, v99
	global_store_dwordx4 v[82:83], v[100:103], off nt
	s_cbranch_vccnz .LBB0_293
	v_mov_b32_e32 v242, 0xbfb8aa3b
	v_pk_mul_f32 v[234:235], v[74:75], v[242:243] op_sel_hi:[1,0]
	v_exp_f32_e32 v234, v234
	v_exp_f32_e32 v235, v235
	v_pk_mul_f32 v[236:237], v[76:77], v[242:243] op_sel_hi:[1,0]
	v_exp_f32_e32 v236, v236
	v_exp_f32_e32 v237, v237
	v_pk_mul_f32 v[238:239], v[78:79], v[242:243] op_sel_hi:[1,0]
	v_exp_f32_e32 v238, v238
	v_exp_f32_e32 v239, v239
	v_pk_mul_f32 v[240:241], v[80:81], v[242:243] op_sel_hi:[1,0]
	v_exp_f32_e32 v240, v240
	v_exp_f32_e32 v241, v241
	v_pk_add_f32 v[234:235], v[234:235], 1.0 op_sel_hi:[1,0]
	v_rcp_f32_e32 v234, v234
	v_rcp_f32_e32 v235, v235
	v_pk_add_f32 v[236:237], v[236:237], 1.0 op_sel_hi:[1,0]
	v_rcp_f32_e32 v236, v236
	v_rcp_f32_e32 v237, v237
	v_pk_add_f32 v[238:239], v[238:239], 1.0 op_sel_hi:[1,0]
	v_rcp_f32_e32 v238, v238
	v_rcp_f32_e32 v239, v239
	v_pk_add_f32 v[240:241], v[240:241], 1.0 op_sel_hi:[1,0]
	v_rcp_f32_e32 v240, v240
	v_rcp_f32_e32 v241, v241
	s_and_b64 vcc, exec, s[6:7]
	s_cbranch_vccnz .Lepg6382_m3
	v_pk_mul_f32 v[74:75], v[74:75], v[234:235]
	v_pk_mul_f32 v[74:75], v[74:75], v[94:95]
	v_pk_mul_f32 v[76:77], v[76:77], v[236:237]
	v_pk_mul_f32 v[76:77], v[76:77], v[96:97]
	v_pk_mul_f32 v[78:79], v[78:79], v[238:239]
	v_pk_mul_f32 v[78:79], v[78:79], v[90:91]
	v_pk_mul_f32 v[80:81], v[80:81], v[240:241]
	v_pk_mul_f32 v[80:81], v[80:81], v[92:93]
	s_branch .Lepg6382_dn
.Lepg6382_m3:
	v_mov_b64_e32 v[74:75], v[234:235]
	v_mov_b64_e32 v[76:77], v[236:237]
	v_mov_b64_e32 v[78:79], v[238:239]
	v_mov_b64_e32 v[80:81], v[240:241]
.Lepg6382_dn:
.LBB0_293:
	v_cvt_pk_bf16_f32 v78, v78, v79
	v_cvt_pk_bf16_f32 v79, v80, v81
	v_cvt_pk_bf16_f32 v80, v74, v75
	v_cvt_pk_bf16_f32 v81, v76, v77
	global_store_dwordx4 v[82:83], v[78:81], off offset:256 nt
	s_and_b64 vcc, exec, s[8:9]
	v_mov_b32_e32 v76, v6
	v_mov_b32_e32 v78, v7
	v_mov_b32_e32 v80, v8
	v_mov_b32_e32 v82, v9
	v_mov_b32_e32 v77, v2
	v_mov_b32_e32 v79, v3
	v_mov_b32_e32 v81, v4
	v_mov_b32_e32 v83, v5
	s_cbranch_vccnz .LBB0_295
	v_mov_b32_e32 v242, 0xbfb8aa3b
	v_pk_mul_f32 v[234:235], v[2:3], v[242:243] op_sel_hi:[1,0]
	v_exp_f32_e32 v234, v234
	v_exp_f32_e32 v235, v235
	v_pk_mul_f32 v[236:237], v[4:5], v[242:243] op_sel_hi:[1,0]
	v_exp_f32_e32 v236, v236
	v_exp_f32_e32 v237, v237
	v_pk_mul_f32 v[238:239], v[6:7], v[242:243] op_sel_hi:[1,0]
	v_exp_f32_e32 v238, v238
	v_exp_f32_e32 v239, v239
	v_pk_mul_f32 v[240:241], v[8:9], v[242:243] op_sel_hi:[1,0]
	v_exp_f32_e32 v240, v240
	v_exp_f32_e32 v241, v241
	v_pk_add_f32 v[234:235], v[234:235], 1.0 op_sel_hi:[1,0]
	v_rcp_f32_e32 v234, v234
	v_rcp_f32_e32 v235, v235
	v_pk_add_f32 v[236:237], v[236:237], 1.0 op_sel_hi:[1,0]
	v_rcp_f32_e32 v236, v236
	v_rcp_f32_e32 v237, v237
	v_pk_add_f32 v[238:239], v[238:239], 1.0 op_sel_hi:[1,0]
	v_rcp_f32_e32 v238, v238
	v_rcp_f32_e32 v239, v239
	v_pk_add_f32 v[240:241], v[240:241], 1.0 op_sel_hi:[1,0]
	v_rcp_f32_e32 v240, v240
	v_rcp_f32_e32 v241, v241
	s_and_b64 vcc, exec, s[6:7]
	s_cbranch_vccnz .Lepg6463_m3
	v_mul_f32_e32 v77, v2, v234
	v_mul_f32_e32 v79, v3, v235
	v_mul_f32_e32 v77, v77, v94
	v_mul_f32_e32 v79, v79, v95
	v_mul_f32_e32 v81, v4, v236
	v_mul_f32_e32 v83, v5, v237
	v_mul_f32_e32 v81, v81, v96
	v_mul_f32_e32 v83, v83, v97
	v_mul_f32_e32 v76, v6, v238
	v_mul_f32_e32 v78, v7, v239
	v_mul_f32_e32 v76, v76, v90
	v_mul_f32_e32 v78, v78, v91
	v_mul_f32_e32 v80, v8, v240
	v_mul_f32_e32 v82, v9, v241
	v_mul_f32_e32 v80, v80, v92
	v_mul_f32_e32 v82, v82, v93
	s_branch .Lepg6463_dn
.Lepg6463_m3:
	v_mov_b32_e32 v77, v234
	v_mov_b32_e32 v79, v235
	v_mov_b32_e32 v81, v236
	v_mov_b32_e32 v83, v237
	v_mov_b32_e32 v76, v238
	v_mov_b32_e32 v78, v239
	v_mov_b32_e32 v80, v240
	v_mov_b32_e32 v82, v241
.Lepg6463_dn:
.LBB0_295:
	v_readlane_b32 s38, v249, 43
	v_readlane_b32 s39, v249, 44
	v_add_u32_e32 v84, 0xb0, v152
	s_and_b64 vcc, exec, s[8:9]
	v_mov_b64_e32 v[74:75], s[38:39]
	v_mad_i64_i32 v[74:75], s[38:39], v84, s76, v[74:75]
	v_lshl_add_u64 v[74:75], v[154:155], 1, v[74:75]
	v_cvt_pk_bf16_f32 v84, v76, v78
	v_cvt_pk_bf16_f32 v85, v80, v82
	v_cvt_pk_bf16_f32 v86, v77, v79
	v_cvt_pk_bf16_f32 v87, v81, v83
	global_store_dwordx4 v[74:75], v[84:87], off nt
	s_cbranch_vccnz .LBB0_297
	v_mov_b32_e32 v242, 0xbfb8aa3b
	v_pk_mul_f32 v[234:235], v[30:31], v[242:243] op_sel_hi:[1,0]
	v_exp_f32_e32 v234, v234
	v_exp_f32_e32 v235, v235
	v_pk_mul_f32 v[236:237], v[32:33], v[242:243] op_sel_hi:[1,0]
	v_exp_f32_e32 v236, v236
	v_exp_f32_e32 v237, v237
	v_pk_mul_f32 v[238:239], v[38:39], v[242:243] op_sel_hi:[1,0]
	v_exp_f32_e32 v238, v238
	v_exp_f32_e32 v239, v239
	v_pk_mul_f32 v[240:241], v[40:41], v[242:243] op_sel_hi:[1,0]
	v_exp_f32_e32 v240, v240
	v_exp_f32_e32 v241, v241
	v_pk_add_f32 v[234:235], v[234:235], 1.0 op_sel_hi:[1,0]
	v_rcp_f32_e32 v234, v234
	v_rcp_f32_e32 v235, v235
	v_pk_add_f32 v[236:237], v[236:237], 1.0 op_sel_hi:[1,0]
	v_rcp_f32_e32 v236, v236
	v_rcp_f32_e32 v237, v237
	v_pk_add_f32 v[238:239], v[238:239], 1.0 op_sel_hi:[1,0]
	v_rcp_f32_e32 v238, v238
	v_rcp_f32_e32 v239, v239
	v_pk_add_f32 v[240:241], v[240:241], 1.0 op_sel_hi:[1,0]
	v_rcp_f32_e32 v240, v240
	v_rcp_f32_e32 v241, v241
	s_and_b64 vcc, exec, s[6:7]
	s_cbranch_vccnz .Lepg6542_m3
	v_pk_mul_f32 v[30:31], v[30:31], v[234:235]
	v_pk_mul_f32 v[30:31], v[30:31], v[94:95]
	v_pk_mul_f32 v[32:33], v[32:33], v[236:237]
	v_pk_mul_f32 v[32:33], v[32:33], v[96:97]
	v_pk_mul_f32 v[38:39], v[38:39], v[238:239]
	v_pk_mul_f32 v[38:39], v[38:39], v[90:91]
	v_pk_mul_f32 v[40:41], v[40:41], v[240:241]
	v_pk_mul_f32 v[40:41], v[40:41], v[92:93]
	s_branch .Lepg6542_dn
.Lepg6542_m3:
	v_mov_b64_e32 v[30:31], v[234:235]
	v_mov_b64_e32 v[32:33], v[236:237]
	v_mov_b64_e32 v[38:39], v[238:239]
	v_mov_b64_e32 v[40:41], v[240:241]
.Lepg6542_dn:
.LBB0_297:
	v_cvt_pk_bf16_f32 v38, v38, v39
	v_cvt_pk_bf16_f32 v39, v40, v41
	v_cvt_pk_bf16_f32 v40, v30, v31
	v_cvt_pk_bf16_f32 v41, v32, v33
	global_store_dwordx4 v[74:75], v[38:41], off offset:256 nt
	s_branch .LBB0_300

.LBB0_718:
	s_add_i32 s0, s4, 0xffffffbd
	s_cmpk_gt_i32 s4, 0x42
	s_cselect_b32 s5, 3, 0
	s_and_b64 s[6:7], s[6:7], exec
	s_cselect_b32 s5, 2, s5
	s_cmp_lt_u32 s0, -8
	s_cselect_b32 s0, s5, 1
	s_cmp_lg_u32 s0, 0
	s_cselect_b64 s[26:27], -1, 0
	s_cmp_eq_u32 s0, 3
	s_cselect_b64 s[6:7], -1, 0
	s_cmp_eq_u32 s0, 0
	v_mov_b32_e32 v157, v70
	v_mov_b32_e32 v172, v71
	v_mov_b32_e32 v174, v72
	v_mov_b32_e32 v176, v73
	v_mov_b32_e32 v171, v66
	v_mov_b32_e32 v173, v67
	v_mov_b32_e32 v175, v68
	v_mov_b32_e32 v177, v69
	s_cbranch_scc1 .LBB0_720
	v_mov_b32_e32 v242, 0xbfb8aa3b
	v_pk_mul_f32 v[234:235], v[66:67], v[242:243] op_sel_hi:[1,0]
	v_exp_f32_e32 v234, v234
	v_exp_f32_e32 v235, v235
	v_pk_mul_f32 v[236:237], v[68:69], v[242:243] op_sel_hi:[1,0]
	v_exp_f32_e32 v236, v236
	v_exp_f32_e32 v237, v237
	v_pk_mul_f32 v[238:239], v[70:71], v[242:243] op_sel_hi:[1,0]
	v_exp_f32_e32 v238, v238
	v_exp_f32_e32 v239, v239
	v_pk_mul_f32 v[240:241], v[72:73], v[242:243] op_sel_hi:[1,0]
	v_exp_f32_e32 v240, v240
	v_exp_f32_e32 v241, v241
	v_pk_add_f32 v[234:235], v[234:235], 1.0 op_sel_hi:[1,0]
	v_rcp_f32_e32 v234, v234
	v_rcp_f32_e32 v235, v235
	v_pk_add_f32 v[236:237], v[236:237], 1.0 op_sel_hi:[1,0]
	v_rcp_f32_e32 v236, v236
	v_rcp_f32_e32 v237, v237
	v_pk_add_f32 v[238:239], v[238:239], 1.0 op_sel_hi:[1,0]
	v_rcp_f32_e32 v238, v238
	v_rcp_f32_e32 v239, v239
	v_pk_add_f32 v[240:241], v[240:241], 1.0 op_sel_hi:[1,0]
	v_rcp_f32_e32 v240, v240
	v_rcp_f32_e32 v241, v241
	s_and_b64 vcc, exec, s[6:7]
	s_cbranch_vccnz .Lepg14431_m3
	s_waitcnt vmcnt(0)
	v_mul_f32_e32 v171, v66, v234
	v_mul_f32_e32 v173, v67, v235
	v_mul_f32_e32 v171, v171, v102
	v_mul_f32_e32 v173, v173, v103
	v_mul_f32_e32 v175, v68, v236
	v_mul_f32_e32 v177, v69, v237
	v_mul_f32_e32 v175, v175, v104
	v_mul_f32_e32 v177, v177, v105
	v_mul_f32_e32 v157, v70, v238
	v_mul_f32_e32 v172, v71, v239
	v_mul_f32_e32 v157, v157, v98
	v_mul_f32_e32 v172, v172, v99
	v_mul_f32_e32 v174, v72, v240
	v_mul_f32_e32 v176, v73, v241
	v_mul_f32_e32 v174, v174, v100
	v_mul_f32_e32 v176, v176, v101
	s_branch .Lepg14431_dn
.Lepg14431_m3:
	v_mov_b32_e32 v171, v234
	v_mov_b32_e32 v173, v235
	v_mov_b32_e32 v175, v236
	v_mov_b32_e32 v177, v237
	v_mov_b32_e32 v157, v238
	v_mov_b32_e32 v172, v239
	v_mov_b32_e32 v174, v240
	v_mov_b32_e32 v176, v241
.Lepg14431_dn:
.LBB0_720:
	v_lshl_or_b32 v158, s4, 8, v167
	v_mov_b64_e32 v[160:161], s[64:65]
	v_ashrrev_i32_e32 v159, 31, v158
	v_mad_i64_i32 v[160:161], s[4:5], v156, s49, v[160:161]
	v_cvt_pk_bf16_f32 v178, v157, v172
	v_cndmask_b32_e64 v157, 0, 1, s[26:27]
	v_lshl_add_u64 v[160:161], v[158:159], 1, v[160:161]
	v_cmp_ne_u32_e64 s[4:5], 1, v157
	s_andn2_b64 vcc, exec, s[26:27]
	v_cvt_pk_bf16_f32 v179, v174, v176
	v_cvt_pk_bf16_f32 v180, v171, v173
	v_cvt_pk_bf16_f32 v181, v175, v177
	global_store_dwordx4 v[160:161], v[178:181], off nt
	s_cbranch_vccnz .LBB0_722
	v_mov_b32_e32 v242, 0xbfb8aa3b
	v_pk_mul_f32 v[234:235], v[130:131], v[242:243] op_sel_hi:[1,0]
	v_exp_f32_e32 v234, v234
	v_exp_f32_e32 v235, v235
	v_pk_mul_f32 v[236:237], v[132:133], v[242:243] op_sel_hi:[1,0]
	v_exp_f32_e32 v236, v236
	v_exp_f32_e32 v237, v237
	v_pk_mul_f32 v[238:239], v[134:135], v[242:243] op_sel_hi:[1,0]
	v_exp_f32_e32 v238, v238
	v_exp_f32_e32 v239, v239
	v_pk_mul_f32 v[240:241], v[136:137], v[242:243] op_sel_hi:[1,0]
	v_exp_f32_e32 v240, v240
	v_exp_f32_e32 v241, v241
	v_pk_add_f32 v[234:235], v[234:235], 1.0 op_sel_hi:[1,0]
	v_rcp_f32_e32 v234, v234
	v_rcp_f32_e32 v235, v235
	v_pk_add_f32 v[236:237], v[236:237], 1.0 op_sel_hi:[1,0]
	v_rcp_f32_e32 v236, v236
	v_rcp_f32_e32 v237, v237
	v_pk_add_f32 v[238:239], v[238:239], 1.0 op_sel_hi:[1,0]
	v_rcp_f32_e32 v238, v238
	v_rcp_f32_e32 v239, v239
	v_pk_add_f32 v[240:241], v[240:241], 1.0 op_sel_hi:[1,0]
	v_rcp_f32_e32 v240, v240
	v_rcp_f32_e32 v241, v241
	s_and_b64 vcc, exec, s[6:7]
	s_cbranch_vccnz .Lepg14512_m3
	v_pk_mul_f32 v[130:131], v[130:131], v[234:235]
	v_pk_mul_f32 v[130:131], v[130:131], v[102:103]
	v_pk_mul_f32 v[132:133], v[132:133], v[236:237]
	v_pk_mul_f32 v[132:133], v[132:133], v[104:105]
	v_pk_mul_f32 v[134:135], v[134:135], v[238:239]
	v_pk_mul_f32 v[134:135], v[134:135], v[98:99]
	v_pk_mul_f32 v[136:137], v[136:137], v[240:241]
	v_pk_mul_f32 v[136:137], v[136:137], v[100:101]
	s_branch .Lepg14512_dn

.Lepg14512_dn:
.LBB0_722:
	v_cvt_pk_bf16_f32 v134, v134, v135
	v_cvt_pk_bf16_f32 v135, v136, v137
	v_cvt_pk_bf16_f32 v136, v130, v131
	v_cvt_pk_bf16_f32 v137, v132, v133
	global_store_dwordx4 v[160:161], v[134:137], off offset:256 nt
	s_and_b64 vcc, exec, s[4:5]
	v_mov_b32_e32 v132, v62
	v_mov_b32_e32 v134, v63
	v_mov_b32_e32 v136, v64
	v_mov_b32_e32 v157, v65
	v_mov_b32_e32 v133, v58
	v_mov_b32_e32 v135, v59
	v_mov_b32_e32 v137, v60
	v_mov_b32_e32 v160, v61
	s_cbranch_vccnz .LBB0_724
	v_mov_b32_e32 v242, 0xbfb8aa3b
	v_pk_mul_f32 v[234:235], v[58:59], v[242:243] op_sel_hi:[1,0]
	v_exp_f32_e32 v234, v234
	v_exp_f32_e32 v235, v235
	v_pk_mul_f32 v[236:237], v[60:61], v[242:243] op_sel_hi:[1,0]
	v_exp_f32_e32 v236, v236
	v_exp_f32_e32 v237, v237
	v_pk_mul_f32 v[238:239], v[62:63], v[242:243] op_sel_hi:[1,0]
	v_exp_f32_e32 v238, v238
	v_exp_f32_e32 v239, v239
	v_pk_mul_f32 v[240:241], v[64:65], v[242:243] op_sel_hi:[1,0]
	v_exp_f32_e32 v240, v240
	v_exp_f32_e32 v241, v241
	v_pk_add_f32 v[234:235], v[234:235], 1.0 op_sel_hi:[1,0]
	v_rcp_f32_e32 v234, v234
	v_rcp_f32_e32 v235, v235
	v_pk_add_f32 v[236:237], v[236:237], 1.0 op_sel_hi:[1,0]
	v_rcp_f32_e32 v236, v236
	v_rcp_f32_e32 v237, v237
	v_pk_add_f32 v[238:239], v[238:239], 1.0 op_sel_hi:[1,0]
	v_rcp_f32_e32 v238, v238
	v_rcp_f32_e32 v239, v239
	v_pk_add_f32 v[240:241], v[240:241], 1.0 op_sel_hi:[1,0]
	v_rcp_f32_e32 v240, v240
	v_rcp_f32_e32 v241, v241
	s_and_b64 vcc, exec, s[6:7]
	s_cbranch_vccnz .Lepg14593_m3
	v_mul_f32_e32 v133, v58, v234
	v_mul_f32_e32 v135, v59, v235
	v_mul_f32_e32 v133, v133, v102
	v_mul_f32_e32 v135, v135, v103
	v_mul_f32_e32 v137, v60, v236
	v_mul_f32_e32 v160, v61, v237
	v_mul_f32_e32 v137, v137, v104
	v_mul_f32_e32 v160, v160, v105
	v_mul_f32_e32 v132, v62, v238
	v_mul_f32_e32 v134, v63, v239
	v_mul_f32_e32 v132, v132, v98
	v_mul_f32_e32 v134, v134, v99
	v_mul_f32_e32 v136, v64, v240
	v_mul_f32_e32 v157, v65, v241
	v_mul_f32_e32 v136, v136, v100
	v_mul_f32_e32 v157, v157, v101
	s_branch .Lepg14593_dn
.Lepg14593_m3:
	v_mov_b32_e32 v133, v234
	v_mov_b32_e32 v135, v235
	v_mov_b32_e32 v137, v236
	v_mov_b32_e32 v160, v237
	v_mov_b32_e32 v132, v238
	v_mov_b32_e32 v134, v239
	v_mov_b32_e32 v136, v240
	v_mov_b32_e32 v157, v241
.Lepg14593_dn:
.LBB0_724:
	v_or_b32_e32 v161, 16, v156
	v_mov_b64_e32 v[130:131], s[64:65]
	v_mad_i64_i32 v[130:131], s[26:27], v161, s49, v[130:131]
	v_lshl_add_u64 v[130:131], v[158:159], 1, v[130:131]
	s_and_b64 vcc, exec, s[4:5]
	v_cvt_pk_bf16_f32 v172, v132, v134
	v_cvt_pk_bf16_f32 v173, v136, v157
	v_cvt_pk_bf16_f32 v174, v133, v135
	v_cvt_pk_bf16_f32 v175, v137, v160
	global_store_dwordx4 v[130:131], v[172:175], off nt
	s_cbranch_vccnz .LBB0_726
	v_mov_b32_e32 v242, 0xbfb8aa3b
	v_pk_mul_f32 v[234:235], v[122:123], v[242:243] op_sel_hi:[1,0]
	v_exp_f32_e32 v234, v234
	v_exp_f32_e32 v235, v235
	v_pk_mul_f32 v[236:237], v[124:125], v[242:243] op_sel_hi:[1,0]
	v_exp_f32_e32 v236, v236
	v_exp_f32_e32 v237, v237
	v_pk_mul_f32 v[238:239], v[126:127], v[242:243] op_sel_hi:[1,0]
	v_exp_f32_e32 v238, v238
	v_exp_f32_e32 v239, v239
	v_pk_mul_f32 v[240:241], v[128:129], v[242:243] op_sel_hi:[1,0]
	v_exp_f32_e32 v240, v240
	v_exp_f32_e32 v241, v241
	v_pk_add_f32 v[234:235], v[234:235], 1.0 op_sel_hi:[1,0]
	v_rcp_f32_e32 v234, v234
	v_rcp_f32_e32 v235, v235
	v_pk_add_f32 v[236:237], v[236:237], 1.0 op_sel_hi:[1,0]
	v_rcp_f32_e32 v236, v236
	v_rcp_f32_e32 v237, v237
	v_pk_add_f32 v[238:239], v[238:239], 1.0 op_sel_hi:[1,0]
	v_rcp_f32_e32 v238, v238
	v_rcp_f32_e32 v239, v239
	v_pk_add_f32 v[240:241], v[240:241], 1.0 op_sel_hi:[1,0]
	v_rcp_f32_e32 v240, v240
	v_rcp_f32_e32 v241, v241
	s_and_b64 vcc, exec, s[6:7]
	s_cbranch_vccnz .Lepg14670_m3
	v_pk_mul_f32 v[122:123], v[122:123], v[234:235]
	v_pk_mul_f32 v[122:123], v[122:123], v[102:103]
	v_pk_mul_f32 v[124:125], v[124:125], v[236:237]
	v_pk_mul_f32 v[124:125], v[124:125], v[104:105]
	v_pk_mul_f32 v[126:127], v[126:127], v[238:239]
	v_pk_mul_f32 v[126:127], v[126:127], v[98:99]
	v_pk_mul_f32 v[128:129], v[128:129], v[240:241]
	v_pk_mul_f32 v[128:129], v[128:129], v[100:101]
	s_branch .Lepg14670_dn

.Lepg14670_dn:
.LBB0_726:
	v_cvt_pk_bf16_f32 v126, v126, v127
	v_cvt_pk_bf16_f32 v127, v128, v129
	v_cvt_pk_bf16_f32 v128, v122, v123
	v_cvt_pk_bf16_f32 v129, v124, v125
	global_store_dwordx4 v[130:131], v[126:129], off offset:256 nt
	s_and_b64 vcc, exec, s[4:5]
	v_mov_b32_e32 v124, v54
	v_mov_b32_e32 v126, v55
	v_mov_b32_e32 v128, v56
	v_mov_b32_e32 v130, v57
	v_mov_b32_e32 v125, v50
	v_mov_b32_e32 v127, v51
	v_mov_b32_e32 v129, v52
	v_mov_b32_e32 v131, v53
	s_cbranch_vccnz .LBB0_728
	v_mov_b32_e32 v242, 0xbfb8aa3b
	v_pk_mul_f32 v[234:235], v[50:51], v[242:243] op_sel_hi:[1,0]
	v_exp_f32_e32 v234, v234
	v_exp_f32_e32 v235, v235
	v_pk_mul_f32 v[236:237], v[52:53], v[242:243] op_sel_hi:[1,0]
	v_exp_f32_e32 v236, v236
	v_exp_f32_e32 v237, v237
	v_pk_mul_f32 v[238:239], v[54:55], v[242:243] op_sel_hi:[1,0]
	v_exp_f32_e32 v238, v238
	v_exp_f32_e32 v239, v239
	v_pk_mul_f32 v[240:241], v[56:57], v[242:243] op_sel_hi:[1,0]
	v_exp_f32_e32 v240, v240
	v_exp_f32_e32 v241, v241
	v_pk_add_f32 v[234:235], v[234:235], 1.0 op_sel_hi:[1,0]
	v_rcp_f32_e32 v234, v234
	v_rcp_f32_e32 v235, v235
	v_pk_add_f32 v[236:237], v[236:237], 1.0 op_sel_hi:[1,0]
	v_rcp_f32_e32 v236, v236
	v_rcp_f32_e32 v237, v237
	v_pk_add_f32 v[238:239], v[238:239], 1.0 op_sel_hi:[1,0]
	v_rcp_f32_e32 v238, v238
	v_rcp_f32_e32 v239, v239
	v_pk_add_f32 v[240:241], v[240:241], 1.0 op_sel_hi:[1,0]
	v_rcp_f32_e32 v240, v240
	v_rcp_f32_e32 v241, v241
	s_and_b64 vcc, exec, s[6:7]
	s_cbranch_vccnz .Lepg14751_m3
	v_mul_f32_e32 v125, v50, v234
	v_mul_f32_e32 v127, v51, v235
	v_mul_f32_e32 v125, v125, v102
	v_mul_f32_e32 v127, v127, v103
	v_mul_f32_e32 v129, v52, v236
	v_mul_f32_e32 v131, v53, v237
	v_mul_f32_e32 v129, v129, v104
	v_mul_f32_e32 v131, v131, v105
	v_mul_f32_e32 v124, v54, v238
	v_mul_f32_e32 v126, v55, v239
	v_mul_f32_e32 v124, v124, v98
	v_mul_f32_e32 v126, v126, v99
	v_mul_f32_e32 v128, v56, v240
	v_mul_f32_e32 v130, v57, v241
	v_mul_f32_e32 v128, v128, v100
	v_mul_f32_e32 v130, v130, v101
	s_branch .Lepg14751_dn

.Lepg14751_dn:
.LBB0_728:
	v_or_b32_e32 v132, 32, v156
	v_mov_b64_e32 v[122:123], s[64:65]
	v_mad_i64_i32 v[122:123], s[26:27], v132, s49, v[122:123]
	v_lshl_add_u64 v[122:123], v[158:159], 1, v[122:123]
	s_and_b64 vcc, exec, s[4:5]
	v_cvt_pk_bf16_f32 v132, v124, v126
	v_cvt_pk_bf16_f32 v133, v128, v130
	v_cvt_pk_bf16_f32 v134, v125, v127
	v_cvt_pk_bf16_f32 v135, v129, v131
	global_store_dwordx4 v[122:123], v[132:135], off nt
	s_cbranch_vccnz .LBB0_730
	v_mov_b32_e32 v242, 0xbfb8aa3b
	v_pk_mul_f32 v[234:235], v[114:115], v[242:243] op_sel_hi:[1,0]
	v_exp_f32_e32 v234, v234
	v_exp_f32_e32 v235, v235
	v_pk_mul_f32 v[236:237], v[116:117], v[242:243] op_sel_hi:[1,0]
	v_exp_f32_e32 v236, v236
	v_exp_f32_e32 v237, v237
	v_pk_mul_f32 v[238:239], v[118:119], v[242:243] op_sel_hi:[1,0]
	v_exp_f32_e32 v238, v238
	v_exp_f32_e32 v239, v239
	v_pk_mul_f32 v[240:241], v[120:121], v[242:243] op_sel_hi:[1,0]
	v_exp_f32_e32 v240, v240
	v_exp_f32_e32 v241, v241
	v_pk_add_f32 v[234:235], v[234:235], 1.0 op_sel_hi:[1,0]
	v_rcp_f32_e32 v234, v234
	v_rcp_f32_e32 v235, v235
	v_pk_add_f32 v[236:237], v[236:237], 1.0 op_sel_hi:[1,0]
	v_rcp_f32_e32 v236, v236
	v_rcp_f32_e32 v237, v237
	v_pk_add_f32 v[238:239], v[238:239], 1.0 op_sel_hi:[1,0]
	v_rcp_f32_e32 v238, v238
	v_rcp_f32_e32 v239, v239
	v_pk_add_f32 v[240:241], v[240:241], 1.0 op_sel_hi:[1,0]
	v_rcp_f32_e32 v240, v240
	v_rcp_f32_e32 v241, v241
	s_and_b64 vcc, exec, s[6:7]
	s_cbranch_vccnz .Lepg14828_m3
	v_pk_mul_f32 v[114:115], v[114:115], v[234:235]
	v_pk_mul_f32 v[114:115], v[114:115], v[102:103]
	v_pk_mul_f32 v[116:117], v[116:117], v[236:237]
	v_pk_mul_f32 v[116:117], v[116:117], v[104:105]
	v_pk_mul_f32 v[118:119], v[118:119], v[238:239]
	v_pk_mul_f32 v[118:119], v[118:119], v[98:99]
	v_pk_mul_f32 v[120:121], v[120:121], v[240:241]
	v_pk_mul_f32 v[120:121], v[120:121], v[100:101]
	s_branch .Lepg14828_dn

.Lepg14828_dn:
.LBB0_730:
	v_cvt_pk_bf16_f32 v118, v118, v119
	v_cvt_pk_bf16_f32 v119, v120, v121
	v_cvt_pk_bf16_f32 v120, v114, v115
	v_cvt_pk_bf16_f32 v121, v116, v117
	global_store_dwordx4 v[122:123], v[118:121], off offset:256 nt
	s_and_b64 vcc, exec, s[4:5]
	v_mov_b32_e32 v116, v46
	v_mov_b32_e32 v118, v47
	v_mov_b32_e32 v120, v48
	v_mov_b32_e32 v122, v49
	v_mov_b32_e32 v117, v42
	v_mov_b32_e32 v119, v43
	v_mov_b32_e32 v121, v44
	v_mov_b32_e32 v123, v45
	s_cbranch_vccnz .LBB0_732
	v_mov_b32_e32 v242, 0xbfb8aa3b
	v_pk_mul_f32 v[234:235], v[42:43], v[242:243] op_sel_hi:[1,0]
	v_exp_f32_e32 v234, v234
	v_exp_f32_e32 v235, v235
	v_pk_mul_f32 v[236:237], v[44:45], v[242:243] op_sel_hi:[1,0]
	v_exp_f32_e32 v236, v236
	v_exp_f32_e32 v237, v237
	v_pk_mul_f32 v[238:239], v[46:47], v[242:243] op_sel_hi:[1,0]
	v_exp_f32_e32 v238, v238
	v_exp_f32_e32 v239, v239
	v_pk_mul_f32 v[240:241], v[48:49], v[242:243] op_sel_hi:[1,0]
	v_exp_f32_e32 v240, v240
	v_exp_f32_e32 v241, v241
	v_pk_add_f32 v[234:235], v[234:235], 1.0 op_sel_hi:[1,0]
	v_rcp_f32_e32 v234, v234
	v_rcp_f32_e32 v235, v235
	v_pk_add_f32 v[236:237], v[236:237], 1.0 op_sel_hi:[1,0]
	v_rcp_f32_e32 v236, v236
	v_rcp_f32_e32 v237, v237
	v_pk_add_f32 v[238:239], v[238:239], 1.0 op_sel_hi:[1,0]
	v_rcp_f32_e32 v238, v238
	v_rcp_f32_e32 v239, v239
	v_pk_add_f32 v[240:241], v[240:241], 1.0 op_sel_hi:[1,0]
	v_rcp_f32_e32 v240, v240
	v_rcp_f32_e32 v241, v241
	s_and_b64 vcc, exec, s[6:7]
	s_cbranch_vccnz .Lepg14909_m3
	v_mul_f32_e32 v117, v42, v234
	v_mul_f32_e32 v119, v43, v235
	v_mul_f32_e32 v117, v117, v102
	v_mul_f32_e32 v119, v119, v103
	v_mul_f32_e32 v121, v44, v236
	v_mul_f32_e32 v123, v45, v237
	v_mul_f32_e32 v121, v121, v104
	v_mul_f32_e32 v123, v123, v105
	v_mul_f32_e32 v116, v46, v238
	v_mul_f32_e32 v118, v47, v239
	v_mul_f32_e32 v116, v116, v98
	v_mul_f32_e32 v118, v118, v99
	v_mul_f32_e32 v120, v48, v240
	v_mul_f32_e32 v122, v49, v241
	v_mul_f32_e32 v120, v120, v100
	v_mul_f32_e32 v122, v122, v101
	s_branch .Lepg14909_dn

.Lepg14909_dn:
.LBB0_732:
	v_or_b32_e32 v124, 48, v156
	v_mov_b64_e32 v[114:115], s[64:65]
	v_mad_i64_i32 v[114:115], s[26:27], v124, s49, v[114:115]
	v_lshl_add_u64 v[114:115], v[158:159], 1, v[114:115]
	s_and_b64 vcc, exec, s[4:5]
	v_cvt_pk_bf16_f32 v124, v116, v118
	v_cvt_pk_bf16_f32 v125, v120, v122
	v_cvt_pk_bf16_f32 v126, v117, v119
	v_cvt_pk_bf16_f32 v127, v121, v123
	global_store_dwordx4 v[114:115], v[124:127], off nt
	s_cbranch_vccnz .LBB0_734
	v_mov_b32_e32 v242, 0xbfb8aa3b
	v_pk_mul_f32 v[234:235], v[106:107], v[242:243] op_sel_hi:[1,0]
	v_exp_f32_e32 v234, v234
	v_exp_f32_e32 v235, v235
	v_pk_mul_f32 v[236:237], v[108:109], v[242:243] op_sel_hi:[1,0]
	v_exp_f32_e32 v236, v236
	v_exp_f32_e32 v237, v237
	v_pk_mul_f32 v[238:239], v[110:111], v[242:243] op_sel_hi:[1,0]
	v_exp_f32_e32 v238, v238
	v_exp_f32_e32 v239, v239
	v_pk_mul_f32 v[240:241], v[112:113], v[242:243] op_sel_hi:[1,0]
	v_exp_f32_e32 v240, v240
	v_exp_f32_e32 v241, v241
	v_pk_add_f32 v[234:235], v[234:235], 1.0 op_sel_hi:[1,0]
	v_rcp_f32_e32 v234, v234
	v_rcp_f32_e32 v235, v235
	v_pk_add_f32 v[236:237], v[236:237], 1.0 op_sel_hi:[1,0]
	v_rcp_f32_e32 v236, v236
	v_rcp_f32_e32 v237, v237
	v_pk_add_f32 v[238:239], v[238:239], 1.0 op_sel_hi:[1,0]
	v_rcp_f32_e32 v238, v238
	v_rcp_f32_e32 v239, v239
	v_pk_add_f32 v[240:241], v[240:241], 1.0 op_sel_hi:[1,0]
	v_rcp_f32_e32 v240, v240
	v_rcp_f32_e32 v241, v241
	s_and_b64 vcc, exec, s[6:7]
	s_cbranch_vccnz .Lepg14986_m3
	v_pk_mul_f32 v[106:107], v[106:107], v[234:235]
	v_pk_mul_f32 v[106:107], v[106:107], v[102:103]
	v_pk_mul_f32 v[108:109], v[108:109], v[236:237]
	v_pk_mul_f32 v[108:109], v[108:109], v[104:105]
	v_pk_mul_f32 v[110:111], v[110:111], v[238:239]
	v_pk_mul_f32 v[110:111], v[110:111], v[98:99]
	v_pk_mul_f32 v[112:113], v[112:113], v[240:241]
	v_pk_mul_f32 v[112:113], v[112:113], v[100:101]
	s_branch .Lepg14986_dn

.Lepg14986_dn:
.LBB0_734:
	v_cvt_pk_bf16_f32 v110, v110, v111
	v_cvt_pk_bf16_f32 v111, v112, v113
	v_cvt_pk_bf16_f32 v112, v106, v107
	v_cvt_pk_bf16_f32 v113, v108, v109
	global_store_dwordx4 v[114:115], v[110:113], off offset:256 nt
	s_and_b64 vcc, exec, s[4:5]
	v_mov_b32_e32 v108, v34
	v_mov_b32_e32 v110, v35
	v_mov_b32_e32 v112, v36
	v_mov_b32_e32 v114, v37
	v_mov_b32_e32 v109, v26
	v_mov_b32_e32 v111, v27
	v_mov_b32_e32 v113, v28
	v_mov_b32_e32 v115, v29
	s_cbranch_vccnz .LBB0_736
	v_mov_b32_e32 v242, 0xbfb8aa3b
	v_pk_mul_f32 v[234:235], v[26:27], v[242:243] op_sel_hi:[1,0]
	v_exp_f32_e32 v234, v234
	v_exp_f32_e32 v235, v235
	v_pk_mul_f32 v[236:237], v[28:29], v[242:243] op_sel_hi:[1,0]
	v_exp_f32_e32 v236, v236
	v_exp_f32_e32 v237, v237
	v_pk_mul_f32 v[238:239], v[34:35], v[242:243] op_sel_hi:[1,0]
	v_exp_f32_e32 v238, v238
	v_exp_f32_e32 v239, v239
	v_pk_mul_f32 v[240:241], v[36:37], v[242:243] op_sel_hi:[1,0]
	v_exp_f32_e32 v240, v240
	v_exp_f32_e32 v241, v241
	v_pk_add_f32 v[234:235], v[234:235], 1.0 op_sel_hi:[1,0]
	v_rcp_f32_e32 v234, v234
	v_rcp_f32_e32 v235, v235
	v_pk_add_f32 v[236:237], v[236:237], 1.0 op_sel_hi:[1,0]
	v_rcp_f32_e32 v236, v236
	v_rcp_f32_e32 v237, v237
	v_pk_add_f32 v[238:239], v[238:239], 1.0 op_sel_hi:[1,0]
	v_rcp_f32_e32 v238, v238
	v_rcp_f32_e32 v239, v239
	v_pk_add_f32 v[240:241], v[240:241], 1.0 op_sel_hi:[1,0]
	v_rcp_f32_e32 v240, v240
	v_rcp_f32_e32 v241, v241
	s_and_b64 vcc, exec, s[6:7]
	s_cbranch_vccnz .Lepg15067_m3
	v_mul_f32_e32 v109, v26, v234
	v_mul_f32_e32 v111, v27, v235
	v_mul_f32_e32 v109, v109, v102
	v_mul_f32_e32 v111, v111, v103
	v_mul_f32_e32 v113, v28, v236
	v_mul_f32_e32 v115, v29, v237
	v_mul_f32_e32 v113, v113, v104
	v_mul_f32_e32 v115, v115, v105
	v_mul_f32_e32 v108, v34, v238
	v_mul_f32_e32 v110, v35, v239
	v_mul_f32_e32 v108, v108, v98
	v_mul_f32_e32 v110, v110, v99
	v_mul_f32_e32 v112, v36, v240
	v_mul_f32_e32 v114, v37, v241
	v_mul_f32_e32 v112, v112, v100
	v_mul_f32_e32 v114, v114, v101
	s_branch .Lepg15067_dn

.Lepg15067_dn:
.LBB0_736:
	v_add_u32_e32 v116, 0x80, v156
	v_mov_b64_e32 v[106:107], s[64:65]
	v_mad_i64_i32 v[106:107], s[26:27], v116, s49, v[106:107]
	v_lshl_add_u64 v[106:107], v[158:159], 1, v[106:107]
	s_and_b64 vcc, exec, s[4:5]
	v_cvt_pk_bf16_f32 v116, v108, v110
	v_cvt_pk_bf16_f32 v117, v112, v114
	v_cvt_pk_bf16_f32 v118, v109, v111
	v_cvt_pk_bf16_f32 v119, v113, v115
	global_store_dwordx4 v[106:107], v[116:119], off nt
	s_cbranch_vccnz .LBB0_738
	v_mov_b32_e32 v242, 0xbfb8aa3b
	v_pk_mul_f32 v[234:235], v[90:91], v[242:243] op_sel_hi:[1,0]
	v_exp_f32_e32 v234, v234
	v_exp_f32_e32 v235, v235
	v_pk_mul_f32 v[236:237], v[92:93], v[242:243] op_sel_hi:[1,0]
	v_exp_f32_e32 v236, v236
	v_exp_f32_e32 v237, v237
	v_pk_mul_f32 v[238:239], v[94:95], v[242:243] op_sel_hi:[1,0]
	v_exp_f32_e32 v238, v238
	v_exp_f32_e32 v239, v239
	v_pk_mul_f32 v[240:241], v[96:97], v[242:243] op_sel_hi:[1,0]
	v_exp_f32_e32 v240, v240
	v_exp_f32_e32 v241, v241
	v_pk_add_f32 v[234:235], v[234:235], 1.0 op_sel_hi:[1,0]
	v_rcp_f32_e32 v234, v234
	v_rcp_f32_e32 v235, v235
	v_pk_add_f32 v[236:237], v[236:237], 1.0 op_sel_hi:[1,0]
	v_rcp_f32_e32 v236, v236
	v_rcp_f32_e32 v237, v237
	v_pk_add_f32 v[238:239], v[238:239], 1.0 op_sel_hi:[1,0]
	v_rcp_f32_e32 v238, v238
	v_rcp_f32_e32 v239, v239
	v_pk_add_f32 v[240:241], v[240:241], 1.0 op_sel_hi:[1,0]
	v_rcp_f32_e32 v240, v240
	v_rcp_f32_e32 v241, v241
	s_and_b64 vcc, exec, s[6:7]
	s_cbranch_vccnz .Lepg15144_m3
	v_pk_mul_f32 v[90:91], v[90:91], v[234:235]
	v_pk_mul_f32 v[90:91], v[90:91], v[102:103]
	v_pk_mul_f32 v[92:93], v[92:93], v[236:237]
	v_pk_mul_f32 v[92:93], v[92:93], v[104:105]
	v_pk_mul_f32 v[94:95], v[94:95], v[238:239]
	v_pk_mul_f32 v[94:95], v[94:95], v[98:99]
	v_pk_mul_f32 v[96:97], v[96:97], v[240:241]
	v_pk_mul_f32 v[96:97], v[96:97], v[100:101]
	s_branch .Lepg15144_dn
.Lepg15144_m3:
	v_mov_b64_e32 v[90:91], v[234:235]
	v_mov_b64_e32 v[92:93], v[236:237]
	v_mov_b64_e32 v[94:95], v[238:239]
	v_mov_b64_e32 v[96:97], v[240:241]
.Lepg15144_dn:
.LBB0_738:
	v_cvt_pk_bf16_f32 v94, v94, v95
	v_cvt_pk_bf16_f32 v95, v96, v97
	v_cvt_pk_bf16_f32 v96, v90, v91
	v_cvt_pk_bf16_f32 v97, v92, v93
	global_store_dwordx4 v[106:107], v[94:97], off offset:256 nt
	s_and_b64 vcc, exec, s[4:5]
	v_mov_b32_e32 v92, v22
	v_mov_b32_e32 v94, v23
	v_mov_b32_e32 v96, v24
	v_mov_b32_e32 v106, v25
	v_mov_b32_e32 v93, v18
	v_mov_b32_e32 v95, v19
	v_mov_b32_e32 v97, v20
	v_mov_b32_e32 v107, v21
	s_cbranch_vccnz .LBB0_740
	v_mov_b32_e32 v242, 0xbfb8aa3b
	v_pk_mul_f32 v[234:235], v[18:19], v[242:243] op_sel_hi:[1,0]
	v_exp_f32_e32 v234, v234
	v_exp_f32_e32 v235, v235
	v_pk_mul_f32 v[236:237], v[20:21], v[242:243] op_sel_hi:[1,0]
	v_exp_f32_e32 v236, v236
	v_exp_f32_e32 v237, v237
	v_pk_mul_f32 v[238:239], v[22:23], v[242:243] op_sel_hi:[1,0]
	v_exp_f32_e32 v238, v238
	v_exp_f32_e32 v239, v239
	v_pk_mul_f32 v[240:241], v[24:25], v[242:243] op_sel_hi:[1,0]
	v_exp_f32_e32 v240, v240
	v_exp_f32_e32 v241, v241
	v_pk_add_f32 v[234:235], v[234:235], 1.0 op_sel_hi:[1,0]
	v_rcp_f32_e32 v234, v234
	v_rcp_f32_e32 v235, v235
	v_pk_add_f32 v[236:237], v[236:237], 1.0 op_sel_hi:[1,0]
	v_rcp_f32_e32 v236, v236
	v_rcp_f32_e32 v237, v237
	v_pk_add_f32 v[238:239], v[238:239], 1.0 op_sel_hi:[1,0]
	v_rcp_f32_e32 v238, v238
	v_rcp_f32_e32 v239, v239
	v_pk_add_f32 v[240:241], v[240:241], 1.0 op_sel_hi:[1,0]
	v_rcp_f32_e32 v240, v240
	v_rcp_f32_e32 v241, v241
	s_and_b64 vcc, exec, s[6:7]
	s_cbranch_vccnz .Lepg15225_m3
	v_mul_f32_e32 v93, v18, v234
	v_mul_f32_e32 v95, v19, v235
	v_mul_f32_e32 v93, v93, v102
	v_mul_f32_e32 v95, v95, v103
	v_mul_f32_e32 v97, v20, v236
	v_mul_f32_e32 v107, v21, v237
	v_mul_f32_e32 v97, v97, v104
	v_mul_f32_e32 v107, v107, v105
	v_mul_f32_e32 v92, v22, v238
	v_mul_f32_e32 v94, v23, v239
	v_mul_f32_e32 v92, v92, v98
	v_mul_f32_e32 v94, v94, v99
	v_mul_f32_e32 v96, v24, v240
	v_mul_f32_e32 v106, v25, v241
	v_mul_f32_e32 v96, v96, v100
	v_mul_f32_e32 v106, v106, v101
	s_branch .Lepg15225_dn
.Lepg15225_m3:
	v_mov_b32_e32 v93, v234
	v_mov_b32_e32 v95, v235
	v_mov_b32_e32 v97, v236
	v_mov_b32_e32 v107, v237
	v_mov_b32_e32 v92, v238
	v_mov_b32_e32 v94, v239
	v_mov_b32_e32 v96, v240
	v_mov_b32_e32 v106, v241
.Lepg15225_dn:
.LBB0_740:
	v_add_u32_e32 v108, 0x90, v156
	v_mov_b64_e32 v[90:91], s[64:65]
	v_mad_i64_i32 v[90:91], s[26:27], v108, s49, v[90:91]
	v_lshl_add_u64 v[90:91], v[158:159], 1, v[90:91]
	s_and_b64 vcc, exec, s[4:5]
	v_cvt_pk_bf16_f32 v108, v92, v94
	v_cvt_pk_bf16_f32 v109, v96, v106
	v_cvt_pk_bf16_f32 v110, v93, v95
	v_cvt_pk_bf16_f32 v111, v97, v107
	global_store_dwordx4 v[90:91], v[108:111], off nt
	s_cbranch_vccnz .LBB0_742
	v_mov_b32_e32 v242, 0xbfb8aa3b
	v_pk_mul_f32 v[234:235], v[82:83], v[242:243] op_sel_hi:[1,0]
	v_exp_f32_e32 v234, v234
	v_exp_f32_e32 v235, v235
	v_pk_mul_f32 v[236:237], v[84:85], v[242:243] op_sel_hi:[1,0]
	v_exp_f32_e32 v236, v236
	v_exp_f32_e32 v237, v237
	v_pk_mul_f32 v[238:239], v[86:87], v[242:243] op_sel_hi:[1,0]
	v_exp_f32_e32 v238, v238
	v_exp_f32_e32 v239, v239
	v_pk_mul_f32 v[240:241], v[88:89], v[242:243] op_sel_hi:[1,0]
	v_exp_f32_e32 v240, v240
	v_exp_f32_e32 v241, v241
	v_pk_add_f32 v[234:235], v[234:235], 1.0 op_sel_hi:[1,0]
	v_rcp_f32_e32 v234, v234
	v_rcp_f32_e32 v235, v235
	v_pk_add_f32 v[236:237], v[236:237], 1.0 op_sel_hi:[1,0]
	v_rcp_f32_e32 v236, v236
	v_rcp_f32_e32 v237, v237
	v_pk_add_f32 v[238:239], v[238:239], 1.0 op_sel_hi:[1,0]
	v_rcp_f32_e32 v238, v238
	v_rcp_f32_e32 v239, v239
	v_pk_add_f32 v[240:241], v[240:241], 1.0 op_sel_hi:[1,0]
	v_rcp_f32_e32 v240, v240
	v_rcp_f32_e32 v241, v241
	s_and_b64 vcc, exec, s[6:7]
	s_cbranch_vccnz .Lepg15302_m3
	v_pk_mul_f32 v[82:83], v[82:83], v[234:235]
	v_pk_mul_f32 v[82:83], v[82:83], v[102:103]
	v_pk_mul_f32 v[84:85], v[84:85], v[236:237]
	v_pk_mul_f32 v[84:85], v[84:85], v[104:105]
	v_pk_mul_f32 v[86:87], v[86:87], v[238:239]
	v_pk_mul_f32 v[86:87], v[86:87], v[98:99]
	v_pk_mul_f32 v[88:89], v[88:89], v[240:241]
	v_pk_mul_f32 v[88:89], v[88:89], v[100:101]
	s_branch .Lepg15302_dn

.Lepg15302_dn:
.LBB0_742:
	v_cvt_pk_bf16_f32 v86, v86, v87
	v_cvt_pk_bf16_f32 v87, v88, v89
	v_cvt_pk_bf16_f32 v88, v82, v83
	v_cvt_pk_bf16_f32 v89, v84, v85
	global_store_dwordx4 v[90:91], v[86:89], off offset:256 nt
	s_and_b64 vcc, exec, s[4:5]
	v_mov_b32_e32 v84, v14
	v_mov_b32_e32 v86, v15
	v_mov_b32_e32 v88, v16
	v_mov_b32_e32 v90, v17
	v_mov_b32_e32 v85, v10
	v_mov_b32_e32 v87, v11
	v_mov_b32_e32 v89, v12
	v_mov_b32_e32 v91, v13
	s_cbranch_vccnz .LBB0_744
	v_mov_b32_e32 v242, 0xbfb8aa3b
	v_pk_mul_f32 v[234:235], v[10:11], v[242:243] op_sel_hi:[1,0]
	v_exp_f32_e32 v234, v234
	v_exp_f32_e32 v235, v235
	v_pk_mul_f32 v[236:237], v[12:13], v[242:243] op_sel_hi:[1,0]
	v_exp_f32_e32 v236, v236
	v_exp_f32_e32 v237, v237
	v_pk_mul_f32 v[238:239], v[14:15], v[242:243] op_sel_hi:[1,0]
	v_exp_f32_e32 v238, v238
	v_exp_f32_e32 v239, v239
	v_pk_mul_f32 v[240:241], v[16:17], v[242:243] op_sel_hi:[1,0]
	v_exp_f32_e32 v240, v240
	v_exp_f32_e32 v241, v241
	v_pk_add_f32 v[234:235], v[234:235], 1.0 op_sel_hi:[1,0]
	v_rcp_f32_e32 v234, v234
	v_rcp_f32_e32 v235, v235
	v_pk_add_f32 v[236:237], v[236:237], 1.0 op_sel_hi:[1,0]
	v_rcp_f32_e32 v236, v236
	v_rcp_f32_e32 v237, v237
	v_pk_add_f32 v[238:239], v[238:239], 1.0 op_sel_hi:[1,0]
	v_rcp_f32_e32 v238, v238
	v_rcp_f32_e32 v239, v239
	v_pk_add_f32 v[240:241], v[240:241], 1.0 op_sel_hi:[1,0]
	v_rcp_f32_e32 v240, v240
	v_rcp_f32_e32 v241, v241
	s_and_b64 vcc, exec, s[6:7]
	s_cbranch_vccnz .Lepg15383_m3
	v_mul_f32_e32 v85, v10, v234
	v_mul_f32_e32 v87, v11, v235
	v_mul_f32_e32 v85, v85, v102
	v_mul_f32_e32 v87, v87, v103
	v_mul_f32_e32 v89, v12, v236
	v_mul_f32_e32 v91, v13, v237
	v_mul_f32_e32 v89, v89, v104
	v_mul_f32_e32 v91, v91, v105
	v_mul_f32_e32 v84, v14, v238
	v_mul_f32_e32 v86, v15, v239
	v_mul_f32_e32 v84, v84, v98
	v_mul_f32_e32 v86, v86, v99
	v_mul_f32_e32 v88, v16, v240
	v_mul_f32_e32 v90, v17, v241
	v_mul_f32_e32 v88, v88, v100
	v_mul_f32_e32 v90, v90, v101
	s_branch .Lepg15383_dn
.Lepg15383_m3:
	v_mov_b32_e32 v85, v234
	v_mov_b32_e32 v87, v235
	v_mov_b32_e32 v89, v236
	v_mov_b32_e32 v91, v237
	v_mov_b32_e32 v84, v238
	v_mov_b32_e32 v86, v239
	v_mov_b32_e32 v88, v240
	v_mov_b32_e32 v90, v241
.Lepg15383_dn:
.LBB0_744:
	v_add_u32_e32 v92, 0xa0, v156
	v_mov_b64_e32 v[82:83], s[64:65]
	v_mad_i64_i32 v[82:83], s[26:27], v92, s49, v[82:83]
	v_lshl_add_u64 v[82:83], v[158:159], 1, v[82:83]
	s_and_b64 vcc, exec, s[4:5]
	v_cvt_pk_bf16_f32 v92, v84, v86
	v_cvt_pk_bf16_f32 v93, v88, v90
	v_cvt_pk_bf16_f32 v94, v85, v87
	v_cvt_pk_bf16_f32 v95, v89, v91
	global_store_dwordx4 v[82:83], v[92:95], off nt
	s_cbranch_vccnz .LBB0_746
	v_mov_b32_e32 v242, 0xbfb8aa3b
	v_pk_mul_f32 v[234:235], v[74:75], v[242:243] op_sel_hi:[1,0]
	v_exp_f32_e32 v234, v234
	v_exp_f32_e32 v235, v235
	v_pk_mul_f32 v[236:237], v[76:77], v[242:243] op_sel_hi:[1,0]
	v_exp_f32_e32 v236, v236
	v_exp_f32_e32 v237, v237
	v_pk_mul_f32 v[238:239], v[78:79], v[242:243] op_sel_hi:[1,0]
	v_exp_f32_e32 v238, v238
	v_exp_f32_e32 v239, v239
	v_pk_mul_f32 v[240:241], v[80:81], v[242:243] op_sel_hi:[1,0]
	v_exp_f32_e32 v240, v240
	v_exp_f32_e32 v241, v241
	v_pk_add_f32 v[234:235], v[234:235], 1.0 op_sel_hi:[1,0]
	v_rcp_f32_e32 v234, v234
	v_rcp_f32_e32 v235, v235
	v_pk_add_f32 v[236:237], v[236:237], 1.0 op_sel_hi:[1,0]
	v_rcp_f32_e32 v236, v236
	v_rcp_f32_e32 v237, v237
	v_pk_add_f32 v[238:239], v[238:239], 1.0 op_sel_hi:[1,0]
	v_rcp_f32_e32 v238, v238
	v_rcp_f32_e32 v239, v239
	v_pk_add_f32 v[240:241], v[240:241], 1.0 op_sel_hi:[1,0]
	v_rcp_f32_e32 v240, v240
	v_rcp_f32_e32 v241, v241
	s_and_b64 vcc, exec, s[6:7]
	s_cbranch_vccnz .Lepg15460_m3
	v_pk_mul_f32 v[74:75], v[74:75], v[234:235]
	v_pk_mul_f32 v[74:75], v[74:75], v[102:103]
	v_pk_mul_f32 v[76:77], v[76:77], v[236:237]
	v_pk_mul_f32 v[76:77], v[76:77], v[104:105]
	v_pk_mul_f32 v[78:79], v[78:79], v[238:239]
	v_pk_mul_f32 v[78:79], v[78:79], v[98:99]
	v_pk_mul_f32 v[80:81], v[80:81], v[240:241]
	v_pk_mul_f32 v[80:81], v[80:81], v[100:101]
	s_branch .Lepg15460_dn

.Lepg15460_dn:
.LBB0_746:
	v_cvt_pk_bf16_f32 v78, v78, v79
	v_cvt_pk_bf16_f32 v79, v80, v81
	v_cvt_pk_bf16_f32 v80, v74, v75
	v_cvt_pk_bf16_f32 v81, v76, v77
	global_store_dwordx4 v[82:83], v[78:81], off offset:256 nt
	s_and_b64 vcc, exec, s[4:5]
	v_mov_b32_e32 v76, v6
	v_mov_b32_e32 v78, v7
	v_mov_b32_e32 v80, v8
	v_mov_b32_e32 v82, v9
	v_mov_b32_e32 v77, v2
	v_mov_b32_e32 v79, v3
	v_mov_b32_e32 v81, v4
	v_mov_b32_e32 v83, v5
	s_cbranch_vccnz .LBB0_748
	v_mov_b32_e32 v242, 0xbfb8aa3b
	v_pk_mul_f32 v[234:235], v[2:3], v[242:243] op_sel_hi:[1,0]
	v_exp_f32_e32 v234, v234
	v_exp_f32_e32 v235, v235
	v_pk_mul_f32 v[236:237], v[4:5], v[242:243] op_sel_hi:[1,0]
	v_exp_f32_e32 v236, v236
	v_exp_f32_e32 v237, v237
	v_pk_mul_f32 v[238:239], v[6:7], v[242:243] op_sel_hi:[1,0]
	v_exp_f32_e32 v238, v238
	v_exp_f32_e32 v239, v239
	v_pk_mul_f32 v[240:241], v[8:9], v[242:243] op_sel_hi:[1,0]
	v_exp_f32_e32 v240, v240
	v_exp_f32_e32 v241, v241
	v_pk_add_f32 v[234:235], v[234:235], 1.0 op_sel_hi:[1,0]
	v_rcp_f32_e32 v234, v234
	v_rcp_f32_e32 v235, v235
	v_pk_add_f32 v[236:237], v[236:237], 1.0 op_sel_hi:[1,0]
	v_rcp_f32_e32 v236, v236
	v_rcp_f32_e32 v237, v237
	v_pk_add_f32 v[238:239], v[238:239], 1.0 op_sel_hi:[1,0]
	v_rcp_f32_e32 v238, v238
	v_rcp_f32_e32 v239, v239
	v_pk_add_f32 v[240:241], v[240:241], 1.0 op_sel_hi:[1,0]
	v_rcp_f32_e32 v240, v240
	v_rcp_f32_e32 v241, v241
	s_and_b64 vcc, exec, s[6:7]
	s_cbranch_vccnz .Lepg15541_m3
	v_mul_f32_e32 v77, v2, v234
	v_mul_f32_e32 v79, v3, v235
	v_mul_f32_e32 v77, v77, v102
	v_mul_f32_e32 v79, v79, v103
	v_mul_f32_e32 v81, v4, v236
	v_mul_f32_e32 v83, v5, v237
	v_mul_f32_e32 v81, v81, v104
	v_mul_f32_e32 v83, v83, v105
	v_mul_f32_e32 v76, v6, v238
	v_mul_f32_e32 v78, v7, v239
	v_mul_f32_e32 v76, v76, v98
	v_mul_f32_e32 v78, v78, v99
	v_mul_f32_e32 v80, v8, v240
	v_mul_f32_e32 v82, v9, v241
	v_mul_f32_e32 v80, v80, v100
	v_mul_f32_e32 v82, v82, v101
	s_branch .Lepg15541_dn

.Lepg15541_dn:
.LBB0_748:
	v_add_u32_e32 v84, 0xb0, v156
	v_mov_b64_e32 v[74:75], s[64:65]
	v_mad_i64_i32 v[74:75], s[26:27], v84, s49, v[74:75]
	v_lshl_add_u64 v[74:75], v[158:159], 1, v[74:75]
	s_and_b64 vcc, exec, s[4:5]
	v_cvt_pk_bf16_f32 v84, v76, v78
	v_cvt_pk_bf16_f32 v85, v80, v82
	v_cvt_pk_bf16_f32 v86, v77, v79
	v_cvt_pk_bf16_f32 v87, v81, v83
	global_store_dwordx4 v[74:75], v[84:87], off nt
	s_cbranch_vccnz .LBB0_750
	v_mov_b32_e32 v242, 0xbfb8aa3b
	v_pk_mul_f32 v[234:235], v[30:31], v[242:243] op_sel_hi:[1,0]
	v_exp_f32_e32 v234, v234
	v_exp_f32_e32 v235, v235
	v_pk_mul_f32 v[236:237], v[32:33], v[242:243] op_sel_hi:[1,0]
	v_exp_f32_e32 v236, v236
	v_exp_f32_e32 v237, v237
	v_pk_mul_f32 v[238:239], v[38:39], v[242:243] op_sel_hi:[1,0]
	v_exp_f32_e32 v238, v238
	v_exp_f32_e32 v239, v239
	v_pk_mul_f32 v[240:241], v[40:41], v[242:243] op_sel_hi:[1,0]
	v_exp_f32_e32 v240, v240
	v_exp_f32_e32 v241, v241
	v_pk_add_f32 v[234:235], v[234:235], 1.0 op_sel_hi:[1,0]
	v_rcp_f32_e32 v234, v234
	v_rcp_f32_e32 v235, v235
	v_pk_add_f32 v[236:237], v[236:237], 1.0 op_sel_hi:[1,0]
	v_rcp_f32_e32 v236, v236
	v_rcp_f32_e32 v237, v237
	v_pk_add_f32 v[238:239], v[238:239], 1.0 op_sel_hi:[1,0]
	v_rcp_f32_e32 v238, v238
	v_rcp_f32_e32 v239, v239
	v_pk_add_f32 v[240:241], v[240:241], 1.0 op_sel_hi:[1,0]
	v_rcp_f32_e32 v240, v240
	v_rcp_f32_e32 v241, v241
	s_and_b64 vcc, exec, s[6:7]
	s_cbranch_vccnz .Lepg15618_m3
	v_pk_mul_f32 v[30:31], v[30:31], v[234:235]
	v_pk_mul_f32 v[30:31], v[30:31], v[102:103]
	v_pk_mul_f32 v[32:33], v[32:33], v[236:237]
	v_pk_mul_f32 v[32:33], v[32:33], v[104:105]
	v_pk_mul_f32 v[38:39], v[38:39], v[238:239]
	v_pk_mul_f32 v[38:39], v[38:39], v[98:99]
	v_pk_mul_f32 v[40:41], v[40:41], v[240:241]
	v_pk_mul_f32 v[40:41], v[40:41], v[100:101]
	s_branch .Lepg15618_dn
